# GEMM K-loops: the lgkmcnt(0) wait after each MFMA segment's opening barrier removed (the ds_reads were already waited before the barrier)
# speedup vs baseline: 1.0105x; 1.0105x over previous
.LBB0_265:
	ds_read_b128 v[142:145], v151
	ds_read_b128 v[146:149], v151 offset:1024
	ds_read_b128 v[154:157], v151 offset:2048
	ds_read_b128 v[158:161], v151 offset:3072
	ds_read_b128 v[162:165], v152
	ds_read_b128 v[166:169], v152 offset:1024
	ds_read_b128 v[176:179], v152 offset:2048
	ds_read_b128 v[180:183], v152 offset:3072
	s_add_u32 s28, s0, 0xfff00080
	s_addc_u32 s29, s1, -1
	s_cmp_eq_u32 s52, 60
	s_cselect_b32 s31, s33, s29
	s_cselect_b32 s30, s47, s28
	s_cselect_b32 s29, s48, s51
	s_cselect_b32 s28, s49, s50
	v_lshl_add_u64 v[170:171], s[0:1], 0, v[138:139]
	s_add_i32 m0, s5, 0xc000
	ds_read_b128 v[184:187], v153
	ds_read_b128 v[188:191], v153 offset:1024
	ds_read_b128 v[192:195], v153 offset:2048
	ds_read_b128 v[196:199], v153 offset:3072
	ds_read_b128 v[200:203], v153 offset:4096
	ds_read_b128 v[204:207], v153 offset:5120
	ds_read_b128 v[208:211], v153 offset:6144
	ds_read_b128 v[212:215], v153 offset:7168
	global_load_lds_dwordx4 v[170:171], off
	v_lshl_add_u64 v[170:171], s[0:1], 0, v[140:141]
	s_add_i32 m0, s5, 0xe000
	s_nop 0
	global_load_lds_dwordx4 v[170:171], off
	s_waitcnt vmcnt(8)
	s_waitcnt lgkmcnt(0)
	s_barrier
	s_setprio 1
	v_mfma_f32_16x16x32_bf16 v[126:129], v[142:145], v[184:187], v[126:129]
	v_mfma_f32_16x16x32_bf16 v[122:125], v[154:157], v[184:187], v[122:125]
	v_mfma_f32_16x16x32_bf16 v[110:113], v[142:145], v[192:195], v[110:113]
	v_mfma_f32_16x16x32_bf16 v[106:109], v[154:157], v[192:195], v[106:109]
	v_mfma_f32_16x16x32_bf16 v[94:97], v[142:145], v[200:203], v[94:97]
	v_mfma_f32_16x16x32_bf16 v[90:93], v[154:157], v[200:203], v[90:93]
	v_mfma_f32_16x16x32_bf16 v[78:81], v[142:145], v[208:211], v[78:81]
	v_mfma_f32_16x16x32_bf16 v[74:77], v[154:157], v[208:211], v[74:77]
	v_mfma_f32_16x16x32_bf16 v[126:129], v[146:149], v[188:191], v[126:129]
	v_mfma_f32_16x16x32_bf16 v[122:125], v[158:161], v[188:191], v[122:125]
	v_mfma_f32_16x16x32_bf16 v[110:113], v[146:149], v[196:199], v[110:113]
	v_mfma_f32_16x16x32_bf16 v[106:109], v[158:161], v[196:199], v[106:109]
	v_mfma_f32_16x16x32_bf16 v[94:97], v[146:149], v[204:207], v[94:97]
	v_mfma_f32_16x16x32_bf16 v[90:93], v[158:161], v[204:207], v[90:93]
	v_mfma_f32_16x16x32_bf16 v[78:81], v[146:149], v[212:215], v[78:81]
	v_mfma_f32_16x16x32_bf16 v[74:77], v[158:161], v[212:215], v[74:77]
	s_setprio 0
	s_setprio 1
	v_mfma_f32_16x16x32_bf16 v[118:121], v[162:165], v[184:187], v[118:121]
	v_mfma_f32_16x16x32_bf16 v[114:117], v[176:179], v[184:187], v[114:117]
	v_mfma_f32_16x16x32_bf16 v[102:105], v[162:165], v[192:195], v[102:105]
	v_mfma_f32_16x16x32_bf16 v[98:101], v[176:179], v[192:195], v[98:101]
	v_mfma_f32_16x16x32_bf16 v[86:89], v[162:165], v[200:203], v[86:89]
	v_mfma_f32_16x16x32_bf16 v[82:85], v[176:179], v[200:203], v[82:85]
	v_mfma_f32_16x16x32_bf16 v[70:73], v[162:165], v[208:211], v[70:73]
	v_mfma_f32_16x16x32_bf16 v[66:69], v[176:179], v[208:211], v[66:69]
	v_mfma_f32_16x16x32_bf16 v[118:121], v[166:169], v[188:191], v[118:121]
	v_mfma_f32_16x16x32_bf16 v[114:117], v[180:183], v[188:191], v[114:117]
	v_mfma_f32_16x16x32_bf16 v[102:105], v[166:169], v[196:199], v[102:105]
	v_mfma_f32_16x16x32_bf16 v[98:101], v[180:183], v[196:199], v[98:101]
	v_mfma_f32_16x16x32_bf16 v[86:89], v[166:169], v[204:207], v[86:89]
	v_mfma_f32_16x16x32_bf16 v[82:85], v[180:183], v[204:207], v[82:85]
	v_mfma_f32_16x16x32_bf16 v[70:73], v[166:169], v[212:215], v[70:73]
	v_mfma_f32_16x16x32_bf16 v[66:69], v[180:183], v[212:215], v[66:69]
	s_setprio 0
	s_barrier
	s_add_i32 s53, s43, s24
	v_lshl_add_u64 v[170:171], s[28:29], 0, v[134:135]
	s_mov_b32 m0, s53
	ds_read_b128 v[184:187], v153 offset:16384
	ds_read_b128 v[188:191], v153 offset:17408
	ds_read_b128 v[192:195], v153 offset:18432
	ds_read_b128 v[196:199], v153 offset:19456
	ds_read_b128 v[200:203], v153 offset:20480
	ds_read_b128 v[204:207], v153 offset:21504
	ds_read_b128 v[208:211], v153 offset:22528
	ds_read_b128 v[212:215], v153 offset:23552
	global_load_lds_dwordx4 v[170:171], off
	s_add_i32 m0, s53, 0x2000
	s_add_u32 s54, s28, 0x100000
	v_lshl_add_u64 v[216:217], s[28:29], 0, v[130:131]
	s_addc_u32 s55, s29, 0
	s_add_i32 s53, s44, s24
	global_load_lds_dwordx4 v[216:217], off
	v_lshl_add_u64 v[218:219], s[54:55], 0, v[134:135]
	s_mov_b32 m0, s53
	v_lshl_add_u64 v[220:221], s[30:31], 0, v[132:133]
	global_load_lds_dwordx4 v[218:219], off
	v_lshl_add_u64 v[218:219], s[54:55], 0, v[130:131]
	s_add_i32 m0, s53, 0x2000
	s_nop 0
	global_load_lds_dwordx4 v[218:219], off
	v_lshl_add_u64 v[218:219], s[30:31], 0, v[136:137]
	s_mov_b32 m0, s5
	s_nop 0
	global_load_lds_dwordx4 v[218:219], off
	s_mov_b32 m0, s34
	s_nop 0
	global_load_lds_dwordx4 v[220:221], off
	s_waitcnt vmcnt(8)
	s_waitcnt lgkmcnt(0)
	s_barrier
	s_setprio 1
	v_mfma_f32_16x16x32_bf16 v[62:65], v[142:145], v[184:187], v[62:65]
	v_mfma_f32_16x16x32_bf16 v[58:61], v[154:157], v[184:187], v[58:61]
	v_mfma_f32_16x16x32_bf16 v[46:49], v[142:145], v[192:195], v[46:49]
	v_mfma_f32_16x16x32_bf16 v[42:45], v[154:157], v[192:195], v[42:45]
	v_mfma_f32_16x16x32_bf16 v[30:33], v[142:145], v[200:203], v[30:33]
	v_mfma_f32_16x16x32_bf16 v[26:29], v[154:157], v[200:203], v[26:29]
	v_mfma_f32_16x16x32_bf16 v[14:17], v[142:145], v[208:211], v[14:17]
	v_mfma_f32_16x16x32_bf16 v[10:13], v[154:157], v[208:211], v[10:13]
	v_mfma_f32_16x16x32_bf16 v[62:65], v[146:149], v[188:191], v[62:65]
	v_mfma_f32_16x16x32_bf16 v[58:61], v[158:161], v[188:191], v[58:61]
	v_mfma_f32_16x16x32_bf16 v[46:49], v[146:149], v[196:199], v[46:49]
	v_mfma_f32_16x16x32_bf16 v[42:45], v[158:161], v[196:199], v[42:45]
	v_mfma_f32_16x16x32_bf16 v[30:33], v[146:149], v[204:207], v[30:33]
	v_mfma_f32_16x16x32_bf16 v[26:29], v[158:161], v[204:207], v[26:29]
	v_mfma_f32_16x16x32_bf16 v[14:17], v[146:149], v[212:215], v[14:17]
	v_mfma_f32_16x16x32_bf16 v[10:13], v[158:161], v[212:215], v[10:13]
	s_setprio 0
	s_setprio 1
	v_mfma_f32_16x16x32_bf16 v[54:57], v[162:165], v[184:187], v[54:57]
	v_mfma_f32_16x16x32_bf16 v[50:53], v[176:179], v[184:187], v[50:53]
	v_mfma_f32_16x16x32_bf16 v[38:41], v[162:165], v[192:195], v[38:41]
	v_mfma_f32_16x16x32_bf16 v[34:37], v[176:179], v[192:195], v[34:37]
	v_mfma_f32_16x16x32_bf16 v[22:25], v[162:165], v[200:203], v[22:25]
	v_mfma_f32_16x16x32_bf16 v[18:21], v[176:179], v[200:203], v[18:21]
	v_mfma_f32_16x16x32_bf16 v[6:9], v[162:165], v[208:211], v[6:9]
	v_mfma_f32_16x16x32_bf16 v[2:5], v[176:179], v[208:211], v[2:5]
	v_mfma_f32_16x16x32_bf16 v[54:57], v[166:169], v[188:191], v[54:57]
	v_mfma_f32_16x16x32_bf16 v[50:53], v[180:183], v[188:191], v[50:53]
	v_mfma_f32_16x16x32_bf16 v[38:41], v[166:169], v[196:199], v[38:41]
	v_mfma_f32_16x16x32_bf16 v[34:37], v[180:183], v[196:199], v[34:37]
	v_mfma_f32_16x16x32_bf16 v[22:25], v[166:169], v[204:207], v[22:25]
	v_mfma_f32_16x16x32_bf16 v[18:21], v[180:183], v[204:207], v[18:21]
	v_mfma_f32_16x16x32_bf16 v[6:9], v[166:169], v[212:215], v[6:9]
	v_mfma_f32_16x16x32_bf16 v[2:5], v[180:183], v[212:215], v[2:5]
	s_setprio 0
	s_barrier
	s_add_i32 s53, 0, 0x18000
	s_add_i32 s54, 0, 0x1c000
	v_add_u32_e32 v158, s53, v150
	v_add_u32_e32 v180, s54, v150
	ds_read_b128 v[142:145], v158
	ds_read_b128 v[146:149], v158 offset:1024
	ds_read_b128 v[154:157], v158 offset:2048
	ds_read_b128 v[158:161], v158 offset:3072
	ds_read_b128 v[162:165], v180
	ds_read_b128 v[166:169], v180 offset:1024
	ds_read_b128 v[176:179], v180 offset:2048
	ds_read_b128 v[180:183], v180 offset:3072
	s_add_u32 s30, s30, 0x100000
	s_addc_u32 s31, s31, 0
	s_mov_b32 m0, s35
	v_lshl_add_u64 v[222:223], s[30:31], 0, v[136:137]
	ds_read_b128 v[184:187], v153 offset:32768
	ds_read_b128 v[188:191], v153 offset:33792
	ds_read_b128 v[192:195], v153 offset:34816
	ds_read_b128 v[196:199], v153 offset:35840
	ds_read_b128 v[200:203], v153 offset:36864
	ds_read_b128 v[204:207], v153 offset:37888
	ds_read_b128 v[208:211], v153 offset:38912
	ds_read_b128 v[212:215], v153 offset:39936
	global_load_lds_dwordx4 v[222:223], off
	v_lshl_add_u64 v[222:223], s[30:31], 0, v[132:133]
	s_mov_b32 m0, s37
	s_nop 0
	global_load_lds_dwordx4 v[222:223], off
	s_waitcnt vmcnt(8)
	s_waitcnt lgkmcnt(0)
	s_barrier
	s_setprio 1
	v_mfma_f32_16x16x32_bf16 v[126:129], v[142:145], v[184:187], v[126:129]
	v_mfma_f32_16x16x32_bf16 v[122:125], v[154:157], v[184:187], v[122:125]
	v_mfma_f32_16x16x32_bf16 v[110:113], v[142:145], v[192:195], v[110:113]
	v_mfma_f32_16x16x32_bf16 v[106:109], v[154:157], v[192:195], v[106:109]
	v_mfma_f32_16x16x32_bf16 v[94:97], v[142:145], v[200:203], v[94:97]
	v_mfma_f32_16x16x32_bf16 v[90:93], v[154:157], v[200:203], v[90:93]
	v_mfma_f32_16x16x32_bf16 v[78:81], v[142:145], v[208:211], v[78:81]
	v_mfma_f32_16x16x32_bf16 v[74:77], v[154:157], v[208:211], v[74:77]
	v_mfma_f32_16x16x32_bf16 v[126:129], v[146:149], v[188:191], v[126:129]
	v_mfma_f32_16x16x32_bf16 v[122:125], v[158:161], v[188:191], v[122:125]
	v_mfma_f32_16x16x32_bf16 v[110:113], v[146:149], v[196:199], v[110:113]
	v_mfma_f32_16x16x32_bf16 v[106:109], v[158:161], v[196:199], v[106:109]
	v_mfma_f32_16x16x32_bf16 v[94:97], v[146:149], v[204:207], v[94:97]
	v_mfma_f32_16x16x32_bf16 v[90:93], v[158:161], v[204:207], v[90:93]
	v_mfma_f32_16x16x32_bf16 v[78:81], v[146:149], v[212:215], v[78:81]
	v_mfma_f32_16x16x32_bf16 v[74:77], v[158:161], v[212:215], v[74:77]
	s_setprio 0
	s_setprio 1
	v_mfma_f32_16x16x32_bf16 v[118:121], v[162:165], v[184:187], v[118:121]
	v_mfma_f32_16x16x32_bf16 v[114:117], v[176:179], v[184:187], v[114:117]
	v_mfma_f32_16x16x32_bf16 v[102:105], v[162:165], v[192:195], v[102:105]
	v_mfma_f32_16x16x32_bf16 v[98:101], v[176:179], v[192:195], v[98:101]
	v_mfma_f32_16x16x32_bf16 v[86:89], v[162:165], v[200:203], v[86:89]
	v_mfma_f32_16x16x32_bf16 v[82:85], v[176:179], v[200:203], v[82:85]
	v_mfma_f32_16x16x32_bf16 v[70:73], v[162:165], v[208:211], v[70:73]
	v_mfma_f32_16x16x32_bf16 v[66:69], v[176:179], v[208:211], v[66:69]
	v_mfma_f32_16x16x32_bf16 v[118:121], v[166:169], v[188:191], v[118:121]
	v_mfma_f32_16x16x32_bf16 v[114:117], v[180:183], v[188:191], v[114:117]
	v_mfma_f32_16x16x32_bf16 v[102:105], v[166:169], v[196:199], v[102:105]
	v_mfma_f32_16x16x32_bf16 v[98:101], v[180:183], v[196:199], v[98:101]
	v_mfma_f32_16x16x32_bf16 v[86:89], v[166:169], v[204:207], v[86:89]
	v_mfma_f32_16x16x32_bf16 v[82:85], v[180:183], v[204:207], v[82:85]
	v_mfma_f32_16x16x32_bf16 v[70:73], v[166:169], v[212:215], v[70:73]
	v_mfma_f32_16x16x32_bf16 v[66:69], v[180:183], v[212:215], v[66:69]
	s_setprio 0
	s_barrier
	s_add_i32 s30, s53, s24
	v_lshl_add_u64 v[170:171], v[170:171], 0, s[12:13]
	s_mov_b32 m0, s30
	ds_read_b128 v[184:187], v153 offset:49152
	ds_read_b128 v[188:191], v153 offset:50176
	ds_read_b128 v[192:195], v153 offset:51200
	ds_read_b128 v[196:199], v153 offset:52224
	ds_read_b128 v[200:203], v153 offset:53248
	ds_read_b128 v[204:207], v153 offset:54272
	ds_read_b128 v[208:211], v153 offset:55296
	ds_read_b128 v[212:215], v153 offset:56320
	global_load_lds_dwordx4 v[170:171], off
	s_add_i32 m0, s30, 0x2000
	s_add_u32 s28, s28, 0x100080
	v_lshl_add_u64 v[170:171], v[216:217], 0, s[12:13]
	s_addc_u32 s29, s29, 0
	s_add_i32 s30, s54, s24
	global_load_lds_dwordx4 v[170:171], off
	v_lshl_add_u64 v[170:171], s[28:29], 0, v[134:135]
	s_mov_b32 m0, s30
	s_nop 0
	global_load_lds_dwordx4 v[170:171], off
	v_lshl_add_u64 v[170:171], s[28:29], 0, v[130:131]
	s_add_i32 m0, s30, 0x2000
	s_nop 0
	global_load_lds_dwordx4 v[170:171], off
	v_lshl_add_u64 v[170:171], v[218:219], 0, s[12:13]
	s_mov_b32 m0, s41
	s_nop 0
	global_load_lds_dwordx4 v[170:171], off
	v_lshl_add_u64 v[170:171], v[220:221], 0, s[12:13]
	s_mov_b32 m0, s42
	s_nop 0
	global_load_lds_dwordx4 v[170:171], off
	s_waitcnt vmcnt(8)
	s_waitcnt lgkmcnt(0)
	s_barrier
	s_setprio 1
	v_mfma_f32_16x16x32_bf16 v[62:65], v[142:145], v[184:187], v[62:65]
	v_mfma_f32_16x16x32_bf16 v[58:61], v[154:157], v[184:187], v[58:61]
	v_mfma_f32_16x16x32_bf16 v[46:49], v[142:145], v[192:195], v[46:49]
	v_mfma_f32_16x16x32_bf16 v[42:45], v[154:157], v[192:195], v[42:45]
	v_mfma_f32_16x16x32_bf16 v[30:33], v[142:145], v[200:203], v[30:33]
	v_mfma_f32_16x16x32_bf16 v[26:29], v[154:157], v[200:203], v[26:29]
	v_mfma_f32_16x16x32_bf16 v[14:17], v[142:145], v[208:211], v[14:17]
	v_mfma_f32_16x16x32_bf16 v[10:13], v[154:157], v[208:211], v[10:13]
	v_mfma_f32_16x16x32_bf16 v[62:65], v[146:149], v[188:191], v[62:65]
	v_mfma_f32_16x16x32_bf16 v[58:61], v[158:161], v[188:191], v[58:61]
	v_mfma_f32_16x16x32_bf16 v[46:49], v[146:149], v[196:199], v[46:49]
	v_mfma_f32_16x16x32_bf16 v[42:45], v[158:161], v[196:199], v[42:45]
	v_mfma_f32_16x16x32_bf16 v[30:33], v[146:149], v[204:207], v[30:33]
	v_mfma_f32_16x16x32_bf16 v[26:29], v[158:161], v[204:207], v[26:29]
	v_mfma_f32_16x16x32_bf16 v[14:17], v[146:149], v[212:215], v[14:17]
	v_mfma_f32_16x16x32_bf16 v[10:13], v[158:161], v[212:215], v[10:13]
	s_setprio 0
	s_setprio 1
	v_mfma_f32_16x16x32_bf16 v[54:57], v[162:165], v[184:187], v[54:57]
	v_mfma_f32_16x16x32_bf16 v[50:53], v[176:179], v[184:187], v[50:53]
	v_mfma_f32_16x16x32_bf16 v[38:41], v[162:165], v[192:195], v[38:41]
	v_mfma_f32_16x16x32_bf16 v[34:37], v[176:179], v[192:195], v[34:37]
	v_mfma_f32_16x16x32_bf16 v[22:25], v[162:165], v[200:203], v[22:25]
	v_mfma_f32_16x16x32_bf16 v[18:21], v[176:179], v[200:203], v[18:21]
	v_mfma_f32_16x16x32_bf16 v[6:9], v[162:165], v[208:211], v[6:9]
	v_mfma_f32_16x16x32_bf16 v[2:5], v[176:179], v[208:211], v[2:5]
	v_mfma_f32_16x16x32_bf16 v[54:57], v[166:169], v[188:191], v[54:57]
	v_mfma_f32_16x16x32_bf16 v[50:53], v[180:183], v[188:191], v[50:53]
	v_mfma_f32_16x16x32_bf16 v[38:41], v[166:169], v[196:199], v[38:41]
	v_mfma_f32_16x16x32_bf16 v[34:37], v[180:183], v[196:199], v[34:37]
	v_mfma_f32_16x16x32_bf16 v[22:25], v[166:169], v[204:207], v[22:25]
	v_mfma_f32_16x16x32_bf16 v[18:21], v[180:183], v[204:207], v[18:21]
	v_mfma_f32_16x16x32_bf16 v[6:9], v[166:169], v[212:215], v[6:9]
	v_mfma_f32_16x16x32_bf16 v[2:5], v[180:183], v[212:215], v[2:5]
	s_setprio 0
	s_barrier
	s_add_i32 s52, s52, 2
	s_add_u32 s0, s0, 0x100
	s_addc_u32 s1, s1, 0
	s_add_u32 s50, s50, 0x100
	s_addc_u32 s51, s51, 0
	s_cmp_gt_u32 s52, 61
	s_cbranch_scc0 .LBB0_265
	s_and_b64 vcc, exec, s[14:15]
	s_cbranch_vccz .LBB0_268
	s_barrier

.LBB0_374:
	ds_read_b128 v[130:133], v188
	ds_read_b128 v[148:151], v188 offset:1024
	ds_read_b128 v[152:155], v188 offset:2048
	ds_read_b128 v[156:159], v188 offset:3072
	ds_read_b128 v[160:163], v189
	ds_read_b128 v[164:167], v189 offset:1024
	ds_read_b128 v[168:171], v189 offset:2048
	ds_read_b128 v[194:197], v189 offset:3072
	s_add_u32 s2, s0, 0xfff00080
	s_addc_u32 s3, s1, -1
	s_cmp_eq_u32 s43, 60
	s_cselect_b32 s39, s5, s3
	s_cselect_b32 s38, s6, s2
	s_cselect_b32 s3, s19, s42
	s_cselect_b32 s2, s21, s33
	v_lshl_add_u64 v[230:231], s[0:1], 0, v[144:145]
	s_add_i32 m0, s25, 0xc000
	ds_read_b128 v[198:201], v190
	ds_read_b128 v[202:205], v190 offset:1024
	ds_read_b128 v[206:209], v190 offset:2048
	ds_read_b128 v[210:213], v190 offset:3072
	ds_read_b128 v[214:217], v190 offset:4096
	ds_read_b128 v[218:221], v190 offset:5120
	ds_read_b128 v[222:225], v190 offset:6144
	ds_read_b128 v[226:229], v190 offset:7168
	global_load_lds_dwordx4 v[230:231], off
	v_lshl_add_u64 v[230:231], s[0:1], 0, v[146:147]
	s_add_i32 m0, s25, 0xe000
	s_nop 0
	global_load_lds_dwordx4 v[230:231], off
	s_waitcnt vmcnt(8)
	s_waitcnt lgkmcnt(0)
	s_barrier
	s_setprio 1
	v_mfma_f32_16x16x32_bf16 v[126:129], v[130:133], v[198:201], v[126:129]
	v_mfma_f32_16x16x32_bf16 v[122:125], v[152:155], v[198:201], v[122:125]
	v_mfma_f32_16x16x32_bf16 v[110:113], v[130:133], v[206:209], v[110:113]
	v_mfma_f32_16x16x32_bf16 v[106:109], v[152:155], v[206:209], v[106:109]
	v_mfma_f32_16x16x32_bf16 v[94:97], v[130:133], v[214:217], v[94:97]
	v_mfma_f32_16x16x32_bf16 v[90:93], v[152:155], v[214:217], v[90:93]
	v_mfma_f32_16x16x32_bf16 v[78:81], v[130:133], v[222:225], v[78:81]
	v_mfma_f32_16x16x32_bf16 v[74:77], v[152:155], v[222:225], v[74:77]
	v_mfma_f32_16x16x32_bf16 v[126:129], v[148:151], v[202:205], v[126:129]
	v_mfma_f32_16x16x32_bf16 v[122:125], v[156:159], v[202:205], v[122:125]
	v_mfma_f32_16x16x32_bf16 v[110:113], v[148:151], v[210:213], v[110:113]
	v_mfma_f32_16x16x32_bf16 v[106:109], v[156:159], v[210:213], v[106:109]
	v_mfma_f32_16x16x32_bf16 v[94:97], v[148:151], v[218:221], v[94:97]
	v_mfma_f32_16x16x32_bf16 v[90:93], v[156:159], v[218:221], v[90:93]
	v_mfma_f32_16x16x32_bf16 v[78:81], v[148:151], v[226:229], v[78:81]
	v_mfma_f32_16x16x32_bf16 v[74:77], v[156:159], v[226:229], v[74:77]
	s_setprio 0
	s_setprio 1
	v_mfma_f32_16x16x32_bf16 v[118:121], v[160:163], v[198:201], v[118:121]
	v_mfma_f32_16x16x32_bf16 v[114:117], v[168:171], v[198:201], v[114:117]
	v_mfma_f32_16x16x32_bf16 v[102:105], v[160:163], v[206:209], v[102:105]
	v_mfma_f32_16x16x32_bf16 v[98:101], v[168:171], v[206:209], v[98:101]
	v_mfma_f32_16x16x32_bf16 v[86:89], v[160:163], v[214:217], v[86:89]
	v_mfma_f32_16x16x32_bf16 v[82:85], v[168:171], v[214:217], v[82:85]
	v_mfma_f32_16x16x32_bf16 v[70:73], v[160:163], v[222:225], v[70:73]
	v_mfma_f32_16x16x32_bf16 v[66:69], v[168:171], v[222:225], v[66:69]
	v_mfma_f32_16x16x32_bf16 v[118:121], v[164:167], v[202:205], v[118:121]
	v_mfma_f32_16x16x32_bf16 v[114:117], v[194:197], v[202:205], v[114:117]
	v_mfma_f32_16x16x32_bf16 v[102:105], v[164:167], v[210:213], v[102:105]
	v_mfma_f32_16x16x32_bf16 v[98:101], v[194:197], v[210:213], v[98:101]
	v_mfma_f32_16x16x32_bf16 v[86:89], v[164:167], v[218:221], v[86:89]
	v_mfma_f32_16x16x32_bf16 v[82:85], v[194:197], v[218:221], v[82:85]
	v_mfma_f32_16x16x32_bf16 v[70:73], v[164:167], v[226:229], v[70:73]
	v_mfma_f32_16x16x32_bf16 v[66:69], v[194:197], v[226:229], v[66:69]
	s_setprio 0
	s_barrier
	s_add_i32 s47, s87, s24
	v_lshl_add_u64 v[230:231], s[2:3], 0, v[136:137]
	s_mov_b32 m0, s47
	ds_read_b128 v[198:201], v190 offset:16384
	ds_read_b128 v[202:205], v190 offset:17408
	ds_read_b128 v[206:209], v190 offset:18432
	ds_read_b128 v[210:213], v190 offset:19456
	ds_read_b128 v[214:217], v190 offset:20480
	ds_read_b128 v[218:221], v190 offset:21504
	ds_read_b128 v[222:225], v190 offset:22528
	ds_read_b128 v[226:229], v190 offset:23552
	global_load_lds_dwordx4 v[230:231], off
	s_add_i32 m0, s47, 0x2000
	s_add_u32 s48, s2, 0x100000
	v_lshl_add_u64 v[232:233], s[2:3], 0, v[140:141]
	s_addc_u32 s49, s3, 0
	s_add_i32 s47, s88, s24
	global_load_lds_dwordx4 v[232:233], off
	v_lshl_add_u64 v[234:235], s[48:49], 0, v[136:137]
	s_mov_b32 m0, s47
	v_lshl_add_u64 v[236:237], s[38:39], 0, v[138:139]
	global_load_lds_dwordx4 v[234:235], off
	v_lshl_add_u64 v[234:235], s[48:49], 0, v[140:141]
	s_add_i32 m0, s47, 0x2000
	s_nop 0
	global_load_lds_dwordx4 v[234:235], off
	v_lshl_add_u64 v[234:235], s[38:39], 0, v[134:135]
	s_mov_b32 m0, s25
	s_nop 0
	global_load_lds_dwordx4 v[234:235], off
	s_mov_b32 m0, s53
	s_nop 0
	global_load_lds_dwordx4 v[236:237], off
	s_waitcnt vmcnt(8)
	s_waitcnt lgkmcnt(0)
	s_barrier
	s_setprio 1
	v_mfma_f32_16x16x32_bf16 v[62:65], v[130:133], v[198:201], v[62:65]
	v_mfma_f32_16x16x32_bf16 v[58:61], v[152:155], v[198:201], v[58:61]
	v_mfma_f32_16x16x32_bf16 v[46:49], v[130:133], v[206:209], v[46:49]
	v_mfma_f32_16x16x32_bf16 v[42:45], v[152:155], v[206:209], v[42:45]
	v_mfma_f32_16x16x32_bf16 v[30:33], v[130:133], v[214:217], v[30:33]
	v_mfma_f32_16x16x32_bf16 v[26:29], v[152:155], v[214:217], v[26:29]
	v_mfma_f32_16x16x32_bf16 v[14:17], v[130:133], v[222:225], v[14:17]
	v_mfma_f32_16x16x32_bf16 v[10:13], v[152:155], v[222:225], v[10:13]
	v_mfma_f32_16x16x32_bf16 v[62:65], v[148:151], v[202:205], v[62:65]
	v_mfma_f32_16x16x32_bf16 v[58:61], v[156:159], v[202:205], v[58:61]
	v_mfma_f32_16x16x32_bf16 v[46:49], v[148:151], v[210:213], v[46:49]
	v_mfma_f32_16x16x32_bf16 v[42:45], v[156:159], v[210:213], v[42:45]
	v_mfma_f32_16x16x32_bf16 v[30:33], v[148:151], v[218:221], v[30:33]
	v_mfma_f32_16x16x32_bf16 v[26:29], v[156:159], v[218:221], v[26:29]
	v_mfma_f32_16x16x32_bf16 v[14:17], v[148:151], v[226:229], v[14:17]
	v_mfma_f32_16x16x32_bf16 v[10:13], v[156:159], v[226:229], v[10:13]
	s_setprio 0
	s_setprio 1
	v_mfma_f32_16x16x32_bf16 v[54:57], v[160:163], v[198:201], v[54:57]
	v_mfma_f32_16x16x32_bf16 v[50:53], v[168:171], v[198:201], v[50:53]
	v_mfma_f32_16x16x32_bf16 v[38:41], v[160:163], v[206:209], v[38:41]
	v_mfma_f32_16x16x32_bf16 v[34:37], v[168:171], v[206:209], v[34:37]
	v_mfma_f32_16x16x32_bf16 v[22:25], v[160:163], v[214:217], v[22:25]
	v_mfma_f32_16x16x32_bf16 v[18:21], v[168:171], v[214:217], v[18:21]
	v_mfma_f32_16x16x32_bf16 v[6:9], v[160:163], v[222:225], v[6:9]
	v_mfma_f32_16x16x32_bf16 v[2:5], v[168:171], v[222:225], v[2:5]
	v_mfma_f32_16x16x32_bf16 v[54:57], v[164:167], v[202:205], v[54:57]
	v_mfma_f32_16x16x32_bf16 v[50:53], v[194:197], v[202:205], v[50:53]
	v_mfma_f32_16x16x32_bf16 v[38:41], v[164:167], v[210:213], v[38:41]
	v_mfma_f32_16x16x32_bf16 v[34:37], v[194:197], v[210:213], v[34:37]
	v_mfma_f32_16x16x32_bf16 v[22:25], v[164:167], v[218:221], v[22:25]
	v_mfma_f32_16x16x32_bf16 v[18:21], v[194:197], v[218:221], v[18:21]
	v_mfma_f32_16x16x32_bf16 v[6:9], v[164:167], v[226:229], v[6:9]
	v_mfma_f32_16x16x32_bf16 v[2:5], v[194:197], v[226:229], v[2:5]
	s_setprio 0
	s_barrier
	s_add_i32 s47, 0, 0x18000
	v_add_u32_e32 v142, s47, v187
	s_add_i32 s48, 0, 0x1c000
	ds_read_b128 v[130:133], v142
	ds_read_b128 v[148:151], v142 offset:1024
	ds_read_b128 v[152:155], v142 offset:2048
	ds_read_b128 v[156:159], v142 offset:3072
	v_add_u32_e32 v142, s48, v187
	ds_read_b128 v[160:163], v142
	ds_read_b128 v[164:167], v142 offset:1024
	ds_read_b128 v[168:171], v142 offset:2048
	ds_read_b128 v[194:197], v142 offset:3072
	s_add_u32 s38, s38, 0x100000
	s_addc_u32 s39, s39, 0
	s_mov_b32 m0, s68
	v_lshl_add_u64 v[238:239], s[38:39], 0, v[134:135]
	ds_read_b128 v[198:201], v190 offset:32768
	ds_read_b128 v[202:205], v190 offset:33792
	ds_read_b128 v[206:209], v190 offset:34816
	ds_read_b128 v[210:213], v190 offset:35840
	ds_read_b128 v[214:217], v190 offset:36864
	ds_read_b128 v[218:221], v190 offset:37888
	ds_read_b128 v[222:225], v190 offset:38912
	ds_read_b128 v[226:229], v190 offset:39936
	global_load_lds_dwordx4 v[238:239], off
	v_lshl_add_u64 v[238:239], s[38:39], 0, v[138:139]
	s_mov_b32 m0, s72
	s_nop 0
	global_load_lds_dwordx4 v[238:239], off
	s_waitcnt vmcnt(8)
	s_waitcnt lgkmcnt(0)
	s_barrier
	s_setprio 1
	v_mfma_f32_16x16x32_bf16 v[126:129], v[130:133], v[198:201], v[126:129]
	v_mfma_f32_16x16x32_bf16 v[122:125], v[152:155], v[198:201], v[122:125]
	v_mfma_f32_16x16x32_bf16 v[110:113], v[130:133], v[206:209], v[110:113]
	v_mfma_f32_16x16x32_bf16 v[106:109], v[152:155], v[206:209], v[106:109]
	v_mfma_f32_16x16x32_bf16 v[94:97], v[130:133], v[214:217], v[94:97]
	v_mfma_f32_16x16x32_bf16 v[90:93], v[152:155], v[214:217], v[90:93]
	v_mfma_f32_16x16x32_bf16 v[78:81], v[130:133], v[222:225], v[78:81]
	v_mfma_f32_16x16x32_bf16 v[74:77], v[152:155], v[222:225], v[74:77]
	v_mfma_f32_16x16x32_bf16 v[126:129], v[148:151], v[202:205], v[126:129]
	v_mfma_f32_16x16x32_bf16 v[122:125], v[156:159], v[202:205], v[122:125]
	v_mfma_f32_16x16x32_bf16 v[110:113], v[148:151], v[210:213], v[110:113]
	v_mfma_f32_16x16x32_bf16 v[106:109], v[156:159], v[210:213], v[106:109]
	v_mfma_f32_16x16x32_bf16 v[94:97], v[148:151], v[218:221], v[94:97]
	v_mfma_f32_16x16x32_bf16 v[90:93], v[156:159], v[218:221], v[90:93]
	v_mfma_f32_16x16x32_bf16 v[78:81], v[148:151], v[226:229], v[78:81]
	v_mfma_f32_16x16x32_bf16 v[74:77], v[156:159], v[226:229], v[74:77]
	s_setprio 0
	s_setprio 1
	v_mfma_f32_16x16x32_bf16 v[118:121], v[160:163], v[198:201], v[118:121]
	v_mfma_f32_16x16x32_bf16 v[114:117], v[168:171], v[198:201], v[114:117]
	v_mfma_f32_16x16x32_bf16 v[102:105], v[160:163], v[206:209], v[102:105]
	v_mfma_f32_16x16x32_bf16 v[98:101], v[168:171], v[206:209], v[98:101]
	v_mfma_f32_16x16x32_bf16 v[86:89], v[160:163], v[214:217], v[86:89]
	v_mfma_f32_16x16x32_bf16 v[82:85], v[168:171], v[214:217], v[82:85]
	v_mfma_f32_16x16x32_bf16 v[70:73], v[160:163], v[222:225], v[70:73]
	v_mfma_f32_16x16x32_bf16 v[66:69], v[168:171], v[222:225], v[66:69]
	v_mfma_f32_16x16x32_bf16 v[118:121], v[164:167], v[202:205], v[118:121]
	v_mfma_f32_16x16x32_bf16 v[114:117], v[194:197], v[202:205], v[114:117]
	v_mfma_f32_16x16x32_bf16 v[102:105], v[164:167], v[210:213], v[102:105]
	v_mfma_f32_16x16x32_bf16 v[98:101], v[194:197], v[210:213], v[98:101]
	v_mfma_f32_16x16x32_bf16 v[86:89], v[164:167], v[218:221], v[86:89]
	v_mfma_f32_16x16x32_bf16 v[82:85], v[194:197], v[218:221], v[82:85]
	v_mfma_f32_16x16x32_bf16 v[70:73], v[164:167], v[226:229], v[70:73]
	v_mfma_f32_16x16x32_bf16 v[66:69], v[194:197], v[226:229], v[66:69]
	s_setprio 0
	s_barrier
	s_add_i32 s38, s47, s24
	v_lshl_add_u64 v[230:231], v[230:231], 0, s[10:11]
	s_mov_b32 m0, s38
	ds_read_b128 v[198:201], v190 offset:49152
	ds_read_b128 v[202:205], v190 offset:50176
	ds_read_b128 v[206:209], v190 offset:51200
	ds_read_b128 v[210:213], v190 offset:52224
	ds_read_b128 v[214:217], v190 offset:53248
	ds_read_b128 v[218:221], v190 offset:54272
	ds_read_b128 v[222:225], v190 offset:55296
	ds_read_b128 v[226:229], v190 offset:56320
	global_load_lds_dwordx4 v[230:231], off
	s_add_i32 m0, s38, 0x2000
	s_add_u32 s2, s2, 0x100080
	v_lshl_add_u64 v[230:231], v[232:233], 0, s[10:11]
	s_addc_u32 s3, s3, 0
	s_add_i32 s38, s48, s24
	global_load_lds_dwordx4 v[230:231], off
	v_lshl_add_u64 v[230:231], s[2:3], 0, v[136:137]
	s_mov_b32 m0, s38
	s_nop 0
	global_load_lds_dwordx4 v[230:231], off
	v_lshl_add_u64 v[230:231], s[2:3], 0, v[140:141]
	s_add_i32 m0, s38, 0x2000
	s_nop 0
	global_load_lds_dwordx4 v[230:231], off
	v_lshl_add_u64 v[230:231], v[234:235], 0, s[10:11]
	s_mov_b32 m0, s77
	s_nop 0
	global_load_lds_dwordx4 v[230:231], off
	v_lshl_add_u64 v[230:231], v[236:237], 0, s[10:11]
	s_mov_b32 m0, s78
	s_nop 0
	global_load_lds_dwordx4 v[230:231], off
	s_waitcnt vmcnt(8)
	s_waitcnt lgkmcnt(0)
	s_barrier
	s_setprio 1
	v_mfma_f32_16x16x32_bf16 v[62:65], v[130:133], v[198:201], v[62:65]
	v_mfma_f32_16x16x32_bf16 v[58:61], v[152:155], v[198:201], v[58:61]
	v_mfma_f32_16x16x32_bf16 v[46:49], v[130:133], v[206:209], v[46:49]
	v_mfma_f32_16x16x32_bf16 v[42:45], v[152:155], v[206:209], v[42:45]
	v_mfma_f32_16x16x32_bf16 v[30:33], v[130:133], v[214:217], v[30:33]
	v_mfma_f32_16x16x32_bf16 v[26:29], v[152:155], v[214:217], v[26:29]
	v_mfma_f32_16x16x32_bf16 v[14:17], v[130:133], v[222:225], v[14:17]
	v_mfma_f32_16x16x32_bf16 v[10:13], v[152:155], v[222:225], v[10:13]
	v_mfma_f32_16x16x32_bf16 v[62:65], v[148:151], v[202:205], v[62:65]
	v_mfma_f32_16x16x32_bf16 v[58:61], v[156:159], v[202:205], v[58:61]
	v_mfma_f32_16x16x32_bf16 v[46:49], v[148:151], v[210:213], v[46:49]
	v_mfma_f32_16x16x32_bf16 v[42:45], v[156:159], v[210:213], v[42:45]
	v_mfma_f32_16x16x32_bf16 v[30:33], v[148:151], v[218:221], v[30:33]
	v_mfma_f32_16x16x32_bf16 v[26:29], v[156:159], v[218:221], v[26:29]
	v_mfma_f32_16x16x32_bf16 v[14:17], v[148:151], v[226:229], v[14:17]
	v_mfma_f32_16x16x32_bf16 v[10:13], v[156:159], v[226:229], v[10:13]
	s_setprio 0
	s_setprio 1
	v_mfma_f32_16x16x32_bf16 v[54:57], v[160:163], v[198:201], v[54:57]
	v_mfma_f32_16x16x32_bf16 v[50:53], v[168:171], v[198:201], v[50:53]
	v_mfma_f32_16x16x32_bf16 v[38:41], v[160:163], v[206:209], v[38:41]
	v_mfma_f32_16x16x32_bf16 v[34:37], v[168:171], v[206:209], v[34:37]
	v_mfma_f32_16x16x32_bf16 v[22:25], v[160:163], v[214:217], v[22:25]
	v_mfma_f32_16x16x32_bf16 v[18:21], v[168:171], v[214:217], v[18:21]
	v_mfma_f32_16x16x32_bf16 v[6:9], v[160:163], v[222:225], v[6:9]
	v_mfma_f32_16x16x32_bf16 v[2:5], v[168:171], v[222:225], v[2:5]
	v_mfma_f32_16x16x32_bf16 v[54:57], v[164:167], v[202:205], v[54:57]
	v_mfma_f32_16x16x32_bf16 v[50:53], v[194:197], v[202:205], v[50:53]
	v_mfma_f32_16x16x32_bf16 v[38:41], v[164:167], v[210:213], v[38:41]
	v_mfma_f32_16x16x32_bf16 v[34:37], v[194:197], v[210:213], v[34:37]
	v_mfma_f32_16x16x32_bf16 v[22:25], v[164:167], v[218:221], v[22:25]
	v_mfma_f32_16x16x32_bf16 v[18:21], v[194:197], v[218:221], v[18:21]
	v_mfma_f32_16x16x32_bf16 v[6:9], v[164:167], v[226:229], v[6:9]
	v_mfma_f32_16x16x32_bf16 v[2:5], v[194:197], v[226:229], v[2:5]
	s_setprio 0
	s_barrier
	s_add_i32 s43, s43, 2
	s_add_u32 s0, s0, 0x100
	s_addc_u32 s1, s1, 0
	s_add_u32 s33, s33, 0x100
	s_addc_u32 s42, s42, 0
	s_cmp_gt_u32 s43, 61
	s_cbranch_scc0 .LBB0_374
	s_and_b64 vcc, exec, s[12:13]
	s_cbranch_vccz .LBB0_377
	s_barrier

.LBB0_755:
	ds_read_b128 v[122:125], v175
	ds_read_b128 v[126:129], v175 offset:1024
	ds_read_b128 v[138:141], v175 offset:2048
	ds_read_b128 v[142:145], v175 offset:3072
	ds_read_b128 v[160:163], v176
	ds_read_b128 v[164:167], v176 offset:1024
	ds_read_b128 v[168:171], v176 offset:2048
	ds_read_b128 v[180:183], v176 offset:3072
	s_add_u32 s2, s0, 0xfff80080
	s_addc_u32 s3, s1, -1
	s_cmp_eq_u32 s35, 28
	s_cselect_b32 s39, s5, s3
	s_cselect_b32 s38, s6, s2
	s_cselect_b32 s3, s16, s33
	s_cselect_b32 s2, s17, s21
	v_lshl_add_u64 v[216:217], s[0:1], 0, v[156:157]
	s_add_i32 m0, s73, 0xc000
	ds_read_b128 v[184:187], v177
	ds_read_b128 v[188:191], v177 offset:1024
	ds_read_b128 v[192:195], v177 offset:2048
	ds_read_b128 v[196:199], v177 offset:3072
	ds_read_b128 v[200:203], v177 offset:4096
	ds_read_b128 v[204:207], v177 offset:5120
	ds_read_b128 v[208:211], v177 offset:6144
	ds_read_b128 v[212:215], v177 offset:7168
	global_load_lds_dwordx4 v[216:217], off
	v_lshl_add_u64 v[216:217], s[0:1], 0, v[158:159]
	s_add_i32 m0, s73, 0xe000
	s_nop 0
	global_load_lds_dwordx4 v[216:217], off
	s_waitcnt vmcnt(8)
	s_waitcnt lgkmcnt(0)
	s_barrier
	s_setprio 1
	v_mfma_i32_16x16x64_i8 v[118:121], v[122:125], v[184:187], v[118:121]
	v_mfma_i32_16x16x64_i8 v[114:117], v[138:141], v[184:187], v[114:117]
	v_mfma_i32_16x16x64_i8 v[102:105], v[122:125], v[192:195], v[102:105]
	v_mfma_i32_16x16x64_i8 v[98:101], v[138:141], v[192:195], v[98:101]
	v_mfma_i32_16x16x64_i8 v[94:97], v[122:125], v[200:203], v[94:97]
	v_mfma_i32_16x16x64_i8 v[86:89], v[138:141], v[200:203], v[86:89]
	v_mfma_i32_16x16x64_i8 v[78:81], v[122:125], v[208:211], v[78:81]
	v_mfma_i32_16x16x64_i8 v[70:73], v[138:141], v[208:211], v[70:73]
	v_mfma_i32_16x16x64_i8 v[118:121], v[126:129], v[188:191], v[118:121]
	v_mfma_i32_16x16x64_i8 v[114:117], v[142:145], v[188:191], v[114:117]
	v_mfma_i32_16x16x64_i8 v[102:105], v[126:129], v[196:199], v[102:105]
	v_mfma_i32_16x16x64_i8 v[98:101], v[142:145], v[196:199], v[98:101]
	v_mfma_i32_16x16x64_i8 v[94:97], v[126:129], v[204:207], v[94:97]
	v_mfma_i32_16x16x64_i8 v[86:89], v[142:145], v[204:207], v[86:89]
	v_mfma_i32_16x16x64_i8 v[78:81], v[126:129], v[212:215], v[78:81]
	v_mfma_i32_16x16x64_i8 v[70:73], v[142:145], v[212:215], v[70:73]
	s_setprio 0
	s_setprio 1
	v_mfma_i32_16x16x64_i8 v[110:113], v[160:163], v[184:187], v[110:113]
	v_mfma_i32_16x16x64_i8 v[106:109], v[168:171], v[184:187], v[106:109]
	v_mfma_i32_16x16x64_i8 v[90:93], v[160:163], v[192:195], v[90:93]
	v_mfma_i32_16x16x64_i8 v[82:85], v[168:171], v[192:195], v[82:85]
	v_mfma_i32_16x16x64_i8 v[74:77], v[160:163], v[200:203], v[74:77]
	v_mfma_i32_16x16x64_i8 v[66:69], v[168:171], v[200:203], v[66:69]
	v_mfma_i32_16x16x64_i8 v[62:65], v[160:163], v[208:211], v[62:65]
	v_mfma_i32_16x16x64_i8 v[58:61], v[168:171], v[208:211], v[58:61]
	v_mfma_i32_16x16x64_i8 v[110:113], v[164:167], v[188:191], v[110:113]
	v_mfma_i32_16x16x64_i8 v[106:109], v[180:183], v[188:191], v[106:109]
	v_mfma_i32_16x16x64_i8 v[90:93], v[164:167], v[196:199], v[90:93]
	v_mfma_i32_16x16x64_i8 v[82:85], v[180:183], v[196:199], v[82:85]
	v_mfma_i32_16x16x64_i8 v[74:77], v[164:167], v[204:207], v[74:77]
	v_mfma_i32_16x16x64_i8 v[66:69], v[180:183], v[204:207], v[66:69]
	v_mfma_i32_16x16x64_i8 v[62:65], v[164:167], v[212:215], v[62:65]
	v_mfma_i32_16x16x64_i8 v[58:61], v[180:183], v[212:215], v[58:61]
	s_setprio 0
	s_barrier
	s_add_i32 s42, s24, s72
	v_lshl_add_u64 v[216:217], s[2:3], 0, v[148:149]
	s_mov_b32 m0, s42
	ds_read_b128 v[184:187], v177 offset:16384
	ds_read_b128 v[188:191], v177 offset:17408
	ds_read_b128 v[192:195], v177 offset:18432
	ds_read_b128 v[196:199], v177 offset:19456
	ds_read_b128 v[200:203], v177 offset:20480
	ds_read_b128 v[204:207], v177 offset:21504
	ds_read_b128 v[208:211], v177 offset:22528
	ds_read_b128 v[212:215], v177 offset:23552
	global_load_lds_dwordx4 v[216:217], off
	s_add_i32 m0, s42, 0x2000
	s_add_u32 s42, s2, 0x80000
	v_lshl_add_u64 v[218:219], s[2:3], 0, v[152:153]
	s_addc_u32 s43, s3, 0
	s_add_i32 s49, s25, s72
	global_load_lds_dwordx4 v[218:219], off
	v_lshl_add_u64 v[220:221], s[42:43], 0, v[148:149]
	s_mov_b32 m0, s49
	v_lshl_add_u64 v[222:223], s[38:39], 0, v[150:151]
	global_load_lds_dwordx4 v[220:221], off
	v_lshl_add_u64 v[220:221], s[42:43], 0, v[152:153]
	s_add_i32 m0, s49, 0x2000
	s_nop 0
	global_load_lds_dwordx4 v[220:221], off
	v_lshl_add_u64 v[220:221], s[38:39], 0, v[146:147]
	s_mov_b32 m0, s73
	s_nop 0
	global_load_lds_dwordx4 v[220:221], off
	s_mov_b32 m0, s74
	s_nop 0
	global_load_lds_dwordx4 v[222:223], off
	s_waitcnt vmcnt(8)
	s_waitcnt lgkmcnt(0)
	s_barrier
	s_setprio 1
	v_mfma_i32_16x16x64_i8 v[54:57], v[122:125], v[184:187], v[54:57]
	v_mfma_i32_16x16x64_i8 v[50:53], v[138:141], v[184:187], v[50:53]
	v_mfma_i32_16x16x64_i8 v[46:49], v[122:125], v[192:195], v[46:49]
	v_mfma_i32_16x16x64_i8 v[38:41], v[138:141], v[192:195], v[38:41]
	v_mfma_i32_16x16x64_i8 v[134:137], v[122:125], v[200:203], v[134:137]
	v_mfma_i32_16x16x64_i8 v[26:29], v[138:141], v[200:203], v[26:29]
	v_mfma_i32_16x16x64_i8 v[14:17], v[138:141], v[208:211], v[14:17]
	v_mfma_i32_16x16x64_i8 v[122:125], v[122:125], v[208:211], v[130:133]
	v_mfma_i32_16x16x64_i8 v[54:57], v[126:129], v[188:191], v[54:57]
	v_mfma_i32_16x16x64_i8 v[50:53], v[142:145], v[188:191], v[50:53]
	v_mfma_i32_16x16x64_i8 v[46:49], v[126:129], v[196:199], v[46:49]
	v_mfma_i32_16x16x64_i8 v[38:41], v[142:145], v[196:199], v[38:41]
	v_mfma_i32_16x16x64_i8 v[130:133], v[126:129], v[204:207], v[134:137]
	v_mfma_i32_16x16x64_i8 v[26:29], v[142:145], v[204:207], v[26:29]
	v_mfma_i32_16x16x64_i8 v[14:17], v[142:145], v[212:215], v[14:17]
	v_mfma_i32_16x16x64_i8 v[122:125], v[126:129], v[212:215], v[122:125]
	s_setprio 0
	s_setprio 1
	v_mfma_i32_16x16x64_i8 v[42:45], v[160:163], v[184:187], v[42:45]
	v_mfma_i32_16x16x64_i8 v[34:37], v[168:171], v[184:187], v[34:37]
	v_mfma_i32_16x16x64_i8 v[30:33], v[160:163], v[192:195], v[30:33]
	v_mfma_i32_16x16x64_i8 v[22:25], v[168:171], v[192:195], v[22:25]
	v_mfma_i32_16x16x64_i8 v[18:21], v[160:163], v[200:203], v[18:21]
	v_mfma_i32_16x16x64_i8 v[10:13], v[168:171], v[200:203], v[10:13]
	v_mfma_i32_16x16x64_i8 v[2:5], v[160:163], v[208:211], v[2:5]
	v_mfma_i32_16x16x64_i8 v[6:9], v[168:171], v[208:211], v[6:9]
	v_mfma_i32_16x16x64_i8 v[42:45], v[164:167], v[188:191], v[42:45]
	v_mfma_i32_16x16x64_i8 v[34:37], v[180:183], v[188:191], v[34:37]
	v_mfma_i32_16x16x64_i8 v[30:33], v[164:167], v[196:199], v[30:33]
	v_mfma_i32_16x16x64_i8 v[22:25], v[180:183], v[196:199], v[22:25]
	v_mfma_i32_16x16x64_i8 v[18:21], v[164:167], v[204:207], v[18:21]
	v_mfma_i32_16x16x64_i8 v[10:13], v[180:183], v[204:207], v[10:13]
	v_mfma_i32_16x16x64_i8 v[2:5], v[164:167], v[212:215], v[2:5]
	v_mfma_i32_16x16x64_i8 v[6:9], v[180:183], v[212:215], v[6:9]
	s_setprio 0
	s_barrier
	s_add_i32 s42, 0, 0x18000
	s_add_i32 s43, 0, 0x1c000
	v_add_u32_e32 v142, s42, v174
	v_add_u32_e32 v154, s43, v174
	ds_read_b128 v[126:129], v142
	ds_read_b128 v[138:141], v142 offset:1024
	ds_read_b128 v[134:137], v142 offset:2048
	ds_read_b128 v[142:145], v142 offset:3072
	ds_read_b128 v[160:163], v154
	ds_read_b128 v[164:167], v154 offset:1024
	ds_read_b128 v[168:171], v154 offset:2048
	ds_read_b128 v[180:183], v154 offset:3072
	s_add_u32 s38, s38, 0x80000
	s_addc_u32 s39, s39, 0
	s_mov_b32 m0, s75
	v_lshl_add_u64 v[224:225], s[38:39], 0, v[146:147]
	ds_read_b128 v[184:187], v177 offset:32768
	ds_read_b128 v[188:191], v177 offset:33792
	ds_read_b128 v[192:195], v177 offset:34816
	ds_read_b128 v[196:199], v177 offset:35840
	ds_read_b128 v[200:203], v177 offset:36864
	ds_read_b128 v[204:207], v177 offset:37888
	ds_read_b128 v[208:211], v177 offset:38912
	ds_read_b128 v[212:215], v177 offset:39936
	global_load_lds_dwordx4 v[224:225], off
	v_lshl_add_u64 v[224:225], s[38:39], 0, v[150:151]
	s_mov_b32 m0, s76
	s_nop 0
	global_load_lds_dwordx4 v[224:225], off
	s_waitcnt vmcnt(8)
	s_waitcnt lgkmcnt(0)
	s_barrier
	s_setprio 1
	v_mfma_i32_16x16x64_i8 v[118:121], v[126:129], v[184:187], v[118:121]
	v_mfma_i32_16x16x64_i8 v[114:117], v[134:137], v[184:187], v[114:117]
	v_mfma_i32_16x16x64_i8 v[102:105], v[126:129], v[192:195], v[102:105]
	v_mfma_i32_16x16x64_i8 v[98:101], v[134:137], v[192:195], v[98:101]
	v_mfma_i32_16x16x64_i8 v[94:97], v[126:129], v[200:203], v[94:97]
	v_mfma_i32_16x16x64_i8 v[86:89], v[134:137], v[200:203], v[86:89]
	v_mfma_i32_16x16x64_i8 v[78:81], v[126:129], v[208:211], v[78:81]
	v_mfma_i32_16x16x64_i8 v[70:73], v[134:137], v[208:211], v[70:73]
	v_mfma_i32_16x16x64_i8 v[118:121], v[138:141], v[188:191], v[118:121]
	v_mfma_i32_16x16x64_i8 v[114:117], v[142:145], v[188:191], v[114:117]
	v_mfma_i32_16x16x64_i8 v[102:105], v[138:141], v[196:199], v[102:105]
	v_mfma_i32_16x16x64_i8 v[98:101], v[142:145], v[196:199], v[98:101]
	v_mfma_i32_16x16x64_i8 v[94:97], v[138:141], v[204:207], v[94:97]
	v_mfma_i32_16x16x64_i8 v[86:89], v[142:145], v[204:207], v[86:89]
	v_mfma_i32_16x16x64_i8 v[78:81], v[138:141], v[212:215], v[78:81]
	v_mfma_i32_16x16x64_i8 v[70:73], v[142:145], v[212:215], v[70:73]
	s_setprio 0
	s_setprio 1
	v_mfma_i32_16x16x64_i8 v[110:113], v[160:163], v[184:187], v[110:113]
	v_mfma_i32_16x16x64_i8 v[106:109], v[168:171], v[184:187], v[106:109]
	v_mfma_i32_16x16x64_i8 v[90:93], v[160:163], v[192:195], v[90:93]
	v_mfma_i32_16x16x64_i8 v[82:85], v[168:171], v[192:195], v[82:85]
	v_mfma_i32_16x16x64_i8 v[74:77], v[160:163], v[200:203], v[74:77]
	v_mfma_i32_16x16x64_i8 v[66:69], v[168:171], v[200:203], v[66:69]
	v_mfma_i32_16x16x64_i8 v[62:65], v[160:163], v[208:211], v[62:65]
	v_mfma_i32_16x16x64_i8 v[58:61], v[168:171], v[208:211], v[58:61]
	v_mfma_i32_16x16x64_i8 v[110:113], v[164:167], v[188:191], v[110:113]
	v_mfma_i32_16x16x64_i8 v[106:109], v[180:183], v[188:191], v[106:109]
	v_mfma_i32_16x16x64_i8 v[90:93], v[164:167], v[196:199], v[90:93]
	v_mfma_i32_16x16x64_i8 v[82:85], v[180:183], v[196:199], v[82:85]
	v_mfma_i32_16x16x64_i8 v[74:77], v[164:167], v[204:207], v[74:77]
	v_mfma_i32_16x16x64_i8 v[66:69], v[180:183], v[204:207], v[66:69]
	v_mfma_i32_16x16x64_i8 v[62:65], v[164:167], v[212:215], v[62:65]
	v_mfma_i32_16x16x64_i8 v[58:61], v[180:183], v[212:215], v[58:61]
	s_setprio 0
	s_barrier
	s_add_i32 s38, s42, s72
	v_lshl_add_u64 v[216:217], v[216:217], 0, s[10:11]
	s_mov_b32 m0, s38
	ds_read_b128 v[184:187], v177 offset:49152
	ds_read_b128 v[188:191], v177 offset:50176
	ds_read_b128 v[192:195], v177 offset:51200
	ds_read_b128 v[196:199], v177 offset:52224
	ds_read_b128 v[200:203], v177 offset:53248
	ds_read_b128 v[204:207], v177 offset:54272
	ds_read_b128 v[208:211], v177 offset:55296
	ds_read_b128 v[212:215], v177 offset:56320
	global_load_lds_dwordx4 v[216:217], off
	s_add_i32 m0, s38, 0x2000
	s_add_u32 s2, s2, 0x80080
	v_lshl_add_u64 v[216:217], v[218:219], 0, s[10:11]
	s_addc_u32 s3, s3, 0
	s_add_i32 s38, s43, s72
	global_load_lds_dwordx4 v[216:217], off
	v_lshl_add_u64 v[216:217], s[2:3], 0, v[148:149]
	s_mov_b32 m0, s38
	s_nop 0
	global_load_lds_dwordx4 v[216:217], off
	v_lshl_add_u64 v[216:217], s[2:3], 0, v[152:153]
	s_add_i32 m0, s38, 0x2000
	s_nop 0
	global_load_lds_dwordx4 v[216:217], off
	v_lshl_add_u64 v[216:217], v[220:221], 0, s[10:11]
	s_mov_b32 m0, s82
	s_nop 0
	global_load_lds_dwordx4 v[216:217], off
	v_lshl_add_u64 v[216:217], v[222:223], 0, s[10:11]
	s_mov_b32 m0, s83
	s_nop 0
	global_load_lds_dwordx4 v[216:217], off
	s_waitcnt vmcnt(8)
	s_waitcnt lgkmcnt(0)
	s_barrier
	s_setprio 1
	v_mfma_i32_16x16x64_i8 v[54:57], v[126:129], v[184:187], v[54:57]
	v_mfma_i32_16x16x64_i8 v[50:53], v[134:137], v[184:187], v[50:53]
	v_mfma_i32_16x16x64_i8 v[46:49], v[126:129], v[192:195], v[46:49]
	v_mfma_i32_16x16x64_i8 v[38:41], v[134:137], v[192:195], v[38:41]
	v_mfma_i32_16x16x64_i8 v[130:133], v[126:129], v[200:203], v[130:133]
	v_mfma_i32_16x16x64_i8 v[26:29], v[134:137], v[200:203], v[26:29]
	v_mfma_i32_16x16x64_i8 v[122:125], v[126:129], v[208:211], v[122:125]
	v_mfma_i32_16x16x64_i8 v[14:17], v[134:137], v[208:211], v[14:17]
	v_mfma_i32_16x16x64_i8 v[54:57], v[138:141], v[188:191], v[54:57]
	v_mfma_i32_16x16x64_i8 v[50:53], v[142:145], v[188:191], v[50:53]
	v_mfma_i32_16x16x64_i8 v[46:49], v[138:141], v[196:199], v[46:49]
	v_mfma_i32_16x16x64_i8 v[38:41], v[142:145], v[196:199], v[38:41]
	v_mfma_i32_16x16x64_i8 v[134:137], v[138:141], v[204:207], v[130:133]
	v_mfma_i32_16x16x64_i8 v[26:29], v[142:145], v[204:207], v[26:29]
	v_mfma_i32_16x16x64_i8 v[130:133], v[138:141], v[212:215], v[122:125]
	v_mfma_i32_16x16x64_i8 v[14:17], v[142:145], v[212:215], v[14:17]
	s_setprio 0
	s_setprio 1
	v_mfma_i32_16x16x64_i8 v[42:45], v[160:163], v[184:187], v[42:45]
	v_mfma_i32_16x16x64_i8 v[34:37], v[168:171], v[184:187], v[34:37]
	v_mfma_i32_16x16x64_i8 v[30:33], v[160:163], v[192:195], v[30:33]
	v_mfma_i32_16x16x64_i8 v[22:25], v[168:171], v[192:195], v[22:25]
	v_mfma_i32_16x16x64_i8 v[18:21], v[160:163], v[200:203], v[18:21]
	v_mfma_i32_16x16x64_i8 v[10:13], v[168:171], v[200:203], v[10:13]
	v_mfma_i32_16x16x64_i8 v[2:5], v[160:163], v[208:211], v[2:5]
	v_mfma_i32_16x16x64_i8 v[6:9], v[168:171], v[208:211], v[6:9]
	v_mfma_i32_16x16x64_i8 v[42:45], v[164:167], v[188:191], v[42:45]
	v_mfma_i32_16x16x64_i8 v[34:37], v[180:183], v[188:191], v[34:37]
	v_mfma_i32_16x16x64_i8 v[30:33], v[164:167], v[196:199], v[30:33]
	v_mfma_i32_16x16x64_i8 v[22:25], v[180:183], v[196:199], v[22:25]
	v_mfma_i32_16x16x64_i8 v[18:21], v[164:167], v[204:207], v[18:21]
	v_mfma_i32_16x16x64_i8 v[10:13], v[180:183], v[204:207], v[10:13]
	v_mfma_i32_16x16x64_i8 v[2:5], v[164:167], v[212:215], v[2:5]
	v_mfma_i32_16x16x64_i8 v[6:9], v[180:183], v[212:215], v[6:9]
	s_setprio 0
	s_barrier
	s_add_i32 s35, s35, 2
	s_add_u32 s0, s0, 0x100
	s_addc_u32 s1, s1, 0
	s_add_u32 s21, s21, 0x100
	s_addc_u32 s33, s33, 0
	s_cmp_gt_u32 s35, 29
	s_cbranch_scc0 .LBB0_755
	s_and_b64 vcc, exec, s[12:13]
	s_cbranch_vccz .LBB0_758
	s_barrier

.LBB0_1493:
	ds_read_b128 v[26:29], v183
	ds_read_b128 v[30:33], v183 offset:1024
	ds_read_b128 v[18:21], v183 offset:2048
	ds_read_b128 v[22:25], v183 offset:3072
	ds_read_b128 v[10:13], v184
	ds_read_b128 v[14:17], v184 offset:1024
	ds_read_b128 v[2:5], v184 offset:2048
	ds_read_b128 v[6:9], v184 offset:3072
	s_add_i32 s55, s50, 2
	s_add_u32 s51, s48, 0xfff80080
	s_addc_u32 s52, s49, -1
	s_cmp_eq_u32 s39, s50
	s_cselect_b32 s50, s33, s43
	s_cselect_b32 s53, s27, s52
	s_cselect_b32 s52, s31, s51
	s_cselect_b32 s51, s29, s47
	v_lshl_add_u64 v[210:211], s[48:49], 0, v[166:167]
	s_add_i32 m0, s62, 0xc000
	ds_read_b128 v[172:175], v185
	ds_read_b128 v[176:179], v185 offset:1024
	ds_read_b128 v[186:189], v185 offset:2048
	ds_read_b128 v[190:193], v185 offset:3072
	ds_read_b128 v[194:197], v185 offset:4096
	ds_read_b128 v[198:201], v185 offset:5120
	ds_read_b128 v[202:205], v185 offset:6144
	ds_read_b128 v[206:209], v185 offset:7168
	global_load_lds_dwordx4 v[210:211], off
	v_lshl_add_u64 v[210:211], s[48:49], 0, v[168:169]
	s_add_i32 m0, s62, 0xe000
	s_nop 0
	global_load_lds_dwordx4 v[210:211], off
	s_waitcnt vmcnt(8)
	s_waitcnt lgkmcnt(0)
	s_barrier
	s_setprio 1
	v_mfma_f32_16x16x128_f8f6f4 v[158:161], v[26:33], v[172:179], v[158:161]
	v_mfma_f32_16x16x128_f8f6f4 v[154:157], v[18:25], v[172:179], v[154:157]
	v_mfma_f32_16x16x128_f8f6f4 v[150:153], v[26:33], v[186:193], v[150:153]
	v_mfma_f32_16x16x128_f8f6f4 v[146:149], v[18:25], v[186:193], v[146:149]
	v_mfma_f32_16x16x128_f8f6f4 v[126:129], v[26:33], v[194:201], v[126:129]
	v_mfma_f32_16x16x128_f8f6f4 v[122:125], v[18:25], v[194:201], v[122:125]
	v_mfma_f32_16x16x128_f8f6f4 v[114:117], v[26:33], v[202:209], v[114:117]
	v_mfma_f32_16x16x128_f8f6f4 v[106:109], v[18:25], v[202:209], v[106:109]
	s_setprio 0
	s_setprio 1
	v_mfma_f32_16x16x128_f8f6f4 v[142:145], v[10:17], v[172:179], v[142:145]
	v_mfma_f32_16x16x128_f8f6f4 v[138:141], v[2:9], v[172:179], v[138:141]
	v_mfma_f32_16x16x128_f8f6f4 v[134:137], v[10:17], v[186:193], v[134:137]
	v_mfma_f32_16x16x128_f8f6f4 v[130:133], v[2:9], v[186:193], v[130:133]
	v_mfma_f32_16x16x128_f8f6f4 v[118:121], v[10:17], v[194:201], v[118:121]
	v_mfma_f32_16x16x128_f8f6f4 v[110:113], v[2:9], v[194:201], v[110:113]
	v_mfma_f32_16x16x128_f8f6f4 v[102:105], v[10:17], v[202:209], v[102:105]
	v_mfma_f32_16x16x128_f8f6f4 v[98:101], v[2:9], v[202:209], v[98:101]
	s_setprio 0
	s_barrier
	s_add_i32 s79, s75, s61
	v_lshl_add_u64 v[172:173], s[50:51], 0, v[162:163]
	s_mov_b32 m0, s79
	ds_read_b128 v[186:189], v185 offset:16384
	ds_read_b128 v[190:193], v185 offset:17408
	ds_read_b128 v[194:197], v185 offset:18432
	ds_read_b128 v[198:201], v185 offset:19456
	ds_read_b128 v[202:205], v185 offset:20480
	ds_read_b128 v[206:209], v185 offset:21504
	ds_read_b128 v[210:213], v185 offset:22528
	ds_read_b128 v[214:217], v185 offset:23552
	global_load_lds_dwordx4 v[172:173], off
	s_add_i32 m0, s79, 0x2000
	s_add_u32 s82, s50, 0x80000
	v_lshl_add_u64 v[174:175], s[50:51], 0, v[164:165]
	s_addc_u32 s83, s51, 0
	s_add_i32 s79, s76, s61
	global_load_lds_dwordx4 v[174:175], off
	v_lshl_add_u64 v[176:177], s[82:83], 0, v[162:163]
	s_mov_b32 m0, s79
	v_lshl_add_u64 v[178:179], s[52:53], 0, v[164:165]
	global_load_lds_dwordx4 v[176:177], off
	v_lshl_add_u64 v[176:177], s[82:83], 0, v[164:165]
	s_add_i32 m0, s79, 0x2000
	s_nop 0
	global_load_lds_dwordx4 v[176:177], off
	v_lshl_add_u64 v[176:177], s[52:53], 0, v[162:163]
	s_mov_b32 m0, s62
	s_nop 0
	global_load_lds_dwordx4 v[176:177], off
	s_mov_b32 m0, s63
	s_nop 0
	global_load_lds_dwordx4 v[178:179], off
	s_waitcnt vmcnt(8)
	s_waitcnt lgkmcnt(0)
	s_barrier
	s_setprio 1
	v_mfma_f32_16x16x128_f8f6f4 v[94:97], v[26:33], v[186:193], v[94:97]
	v_mfma_f32_16x16x128_f8f6f4 v[90:93], v[18:25], v[186:193], v[90:93]
	v_mfma_f32_16x16x128_f8f6f4 v[82:85], v[26:33], v[194:201], v[82:85]
	v_mfma_f32_16x16x128_f8f6f4 v[74:77], v[18:25], v[194:201], v[74:77]
	v_mfma_f32_16x16x128_f8f6f4 v[66:69], v[26:33], v[202:209], v[66:69]
	v_mfma_f32_16x16x128_f8f6f4 v[58:61], v[18:25], v[202:209], v[58:61]
	v_mfma_f32_16x16x128_f8f6f4 v[50:53], v[26:33], v[210:217], v[50:53]
	v_mfma_f32_16x16x128_f8f6f4 v[42:45], v[18:25], v[210:217], v[42:45]
	s_setprio 0
	s_setprio 1
	v_mfma_f32_16x16x128_f8f6f4 v[86:89], v[10:17], v[186:193], v[86:89]
	v_mfma_f32_16x16x128_f8f6f4 v[78:81], v[2:9], v[186:193], v[78:81]
	v_mfma_f32_16x16x128_f8f6f4 v[70:73], v[10:17], v[194:201], v[70:73]
	v_mfma_f32_16x16x128_f8f6f4 v[62:65], v[2:9], v[194:201], v[62:65]
	v_mfma_f32_16x16x128_f8f6f4 v[54:57], v[10:17], v[202:209], v[54:57]
	v_mfma_f32_16x16x128_f8f6f4 v[46:49], v[2:9], v[202:209], v[46:49]
	v_mfma_f32_16x16x128_f8f6f4 v[38:41], v[10:17], v[210:217], v[38:41]
	v_mfma_f32_16x16x128_f8f6f4 v[34:37], v[2:9], v[210:217], v[34:37]
	s_setprio 0
	s_barrier
	s_add_i32 s79, 0, 0x18000
	s_add_i32 s82, 0, 0x1c000
	v_add_u32_e32 v14, s79, v182
	v_add_u32_e32 v30, s82, v182
	ds_read_b128 v[2:5], v14
	ds_read_b128 v[6:9], v14 offset:1024
	ds_read_b128 v[10:13], v14 offset:2048
	ds_read_b128 v[14:17], v14 offset:3072
	ds_read_b128 v[18:21], v30
	ds_read_b128 v[22:25], v30 offset:1024
	ds_read_b128 v[26:29], v30 offset:2048
	ds_read_b128 v[30:33], v30 offset:3072
	s_add_u32 s52, s52, 0x80000
	s_addc_u32 s53, s53, 0
	s_mov_b32 m0, s64
	v_lshl_add_u64 v[218:219], s[52:53], 0, v[162:163]
	ds_read_b128 v[186:189], v185 offset:32768
	ds_read_b128 v[190:193], v185 offset:33792
	ds_read_b128 v[194:197], v185 offset:34816
	ds_read_b128 v[198:201], v185 offset:35840
	ds_read_b128 v[202:205], v185 offset:36864
	ds_read_b128 v[206:209], v185 offset:37888
	ds_read_b128 v[210:213], v185 offset:38912
	ds_read_b128 v[214:217], v185 offset:39936
	global_load_lds_dwordx4 v[218:219], off
	v_lshl_add_u64 v[218:219], s[52:53], 0, v[164:165]
	s_mov_b32 m0, s65
	s_nop 0
	global_load_lds_dwordx4 v[218:219], off
	s_waitcnt vmcnt(8)
	s_waitcnt lgkmcnt(0)
	s_barrier
	s_setprio 1
	v_mfma_f32_16x16x128_f8f6f4 v[158:161], v[2:9], v[186:193], v[158:161]
	v_mfma_f32_16x16x128_f8f6f4 v[154:157], v[10:17], v[186:193], v[154:157]
	v_mfma_f32_16x16x128_f8f6f4 v[150:153], v[2:9], v[194:201], v[150:153]
	v_mfma_f32_16x16x128_f8f6f4 v[146:149], v[10:17], v[194:201], v[146:149]
	v_mfma_f32_16x16x128_f8f6f4 v[126:129], v[2:9], v[202:209], v[126:129]
	v_mfma_f32_16x16x128_f8f6f4 v[122:125], v[10:17], v[202:209], v[122:125]
	v_mfma_f32_16x16x128_f8f6f4 v[114:117], v[2:9], v[210:217], v[114:117]
	v_mfma_f32_16x16x128_f8f6f4 v[106:109], v[10:17], v[210:217], v[106:109]
	s_setprio 0
	s_setprio 1
	v_mfma_f32_16x16x128_f8f6f4 v[142:145], v[18:25], v[186:193], v[142:145]
	v_mfma_f32_16x16x128_f8f6f4 v[138:141], v[26:33], v[186:193], v[138:141]
	v_mfma_f32_16x16x128_f8f6f4 v[134:137], v[18:25], v[194:201], v[134:137]
	v_mfma_f32_16x16x128_f8f6f4 v[130:133], v[26:33], v[194:201], v[130:133]
	v_mfma_f32_16x16x128_f8f6f4 v[118:121], v[18:25], v[202:209], v[118:121]
	v_mfma_f32_16x16x128_f8f6f4 v[110:113], v[26:33], v[202:209], v[110:113]
	v_mfma_f32_16x16x128_f8f6f4 v[102:105], v[18:25], v[210:217], v[102:105]
	v_mfma_f32_16x16x128_f8f6f4 v[98:101], v[26:33], v[210:217], v[98:101]
	s_setprio 0
	s_barrier
	s_add_i32 s52, s79, s61
	v_lshl_add_u64 v[172:173], v[172:173], 0, s[12:13]
	s_mov_b32 m0, s52
	ds_read_b128 v[186:189], v185 offset:49152
	ds_read_b128 v[190:193], v185 offset:50176
	ds_read_b128 v[194:197], v185 offset:51200
	ds_read_b128 v[198:201], v185 offset:52224
	ds_read_b128 v[202:205], v185 offset:53248
	ds_read_b128 v[206:209], v185 offset:54272
	ds_read_b128 v[210:213], v185 offset:55296
	ds_read_b128 v[214:217], v185 offset:56320
	global_load_lds_dwordx4 v[172:173], off
	s_add_i32 m0, s52, 0x2000
	s_add_u32 s50, s50, 0x80080
	v_lshl_add_u64 v[172:173], v[174:175], 0, s[12:13]
	s_addc_u32 s51, s51, 0
	s_add_i32 s52, s82, s61
	global_load_lds_dwordx4 v[172:173], off
	v_lshl_add_u64 v[172:173], s[50:51], 0, v[162:163]
	s_mov_b32 m0, s52
	s_nop 0
	global_load_lds_dwordx4 v[172:173], off
	v_lshl_add_u64 v[172:173], s[50:51], 0, v[164:165]
	s_add_i32 m0, s52, 0x2000
	s_nop 0
	global_load_lds_dwordx4 v[172:173], off
	v_lshl_add_u64 v[172:173], v[176:177], 0, s[12:13]
	s_mov_b32 m0, s70
	s_nop 0
	global_load_lds_dwordx4 v[172:173], off
	v_lshl_add_u64 v[172:173], v[178:179], 0, s[12:13]
	s_mov_b32 m0, s71
	s_nop 0
	global_load_lds_dwordx4 v[172:173], off
	s_waitcnt vmcnt(8)
	s_waitcnt lgkmcnt(0)
	s_barrier
	s_setprio 1
	v_mfma_f32_16x16x128_f8f6f4 v[94:97], v[2:9], v[186:193], v[94:97]
	v_mfma_f32_16x16x128_f8f6f4 v[90:93], v[10:17], v[186:193], v[90:93]
	v_mfma_f32_16x16x128_f8f6f4 v[82:85], v[2:9], v[194:201], v[82:85]
	v_mfma_f32_16x16x128_f8f6f4 v[74:77], v[10:17], v[194:201], v[74:77]
	v_mfma_f32_16x16x128_f8f6f4 v[66:69], v[2:9], v[202:209], v[66:69]
	v_mfma_f32_16x16x128_f8f6f4 v[58:61], v[10:17], v[202:209], v[58:61]
	v_mfma_f32_16x16x128_f8f6f4 v[50:53], v[2:9], v[210:217], v[50:53]
	v_mfma_f32_16x16x128_f8f6f4 v[42:45], v[10:17], v[210:217], v[42:45]
	s_setprio 0
	s_setprio 1
	v_mfma_f32_16x16x128_f8f6f4 v[86:89], v[18:25], v[186:193], v[86:89]
	v_mfma_f32_16x16x128_f8f6f4 v[78:81], v[26:33], v[186:193], v[78:81]
	v_mfma_f32_16x16x128_f8f6f4 v[70:73], v[18:25], v[194:201], v[70:73]
	v_mfma_f32_16x16x128_f8f6f4 v[62:65], v[26:33], v[194:201], v[62:65]
	v_mfma_f32_16x16x128_f8f6f4 v[54:57], v[18:25], v[202:209], v[54:57]
	v_mfma_f32_16x16x128_f8f6f4 v[46:49], v[26:33], v[202:209], v[46:49]
	v_mfma_f32_16x16x128_f8f6f4 v[38:41], v[18:25], v[210:217], v[38:41]
	v_mfma_f32_16x16x128_f8f6f4 v[34:37], v[26:33], v[210:217], v[34:37]
	s_setprio 0
	s_barrier
	s_add_u32 s48, s48, 0x100
	s_addc_u32 s49, s49, 0
	s_add_u32 s43, s43, 0x100
	s_addc_u32 s47, s47, 0
	s_cmp_ge_i32 s55, s42
	s_mov_b32 s50, s55
	s_cbranch_scc0 .LBB0_1493
	s_and_b64 vcc, exec, s[14:15]
	s_cbranch_vccz .LBB0_1496
	s_barrier

.LBB0_1638:
	ds_read_b128 v[142:145], v160
	ds_read_b128 v[168:171], v160 offset:1024
	ds_read_b128 v[172:175], v160 offset:2048
	ds_read_b128 v[180:183], v160 offset:3072
	ds_read_b128 v[184:187], v161
	ds_read_b128 v[188:191], v161 offset:1024
	ds_read_b128 v[192:195], v161 offset:2048
	ds_read_b128 v[196:199], v161 offset:3072
	s_add_u32 s34, s30, 0xfff80080
	s_addc_u32 s35, s31, -1
	s_cmp_eq_u32 s70, 28
	s_cselect_b32 s39, s15, s35
	s_cselect_b32 s38, s27, s34
	s_cselect_b32 s35, s17, s69
	s_cselect_b32 s34, s33, s68
	v_lshl_add_u64 v[146:147], s[30:31], 0, v[138:139]
	s_add_i32 m0, s29, 0xc000
	ds_read_b128 v[200:203], v165
	ds_read_b128 v[204:207], v165 offset:1024
	ds_read_b128 v[208:211], v165 offset:2048
	ds_read_b128 v[212:215], v165 offset:3072
	ds_read_b128 v[216:219], v165 offset:4096
	ds_read_b128 v[220:223], v165 offset:5120
	ds_read_b128 v[224:227], v165 offset:6144
	ds_read_b128 v[228:231], v165 offset:7168
	global_load_lds_dwordx4 v[146:147], off
	v_lshl_add_u64 v[146:147], s[30:31], 0, v[140:141]
	s_add_i32 m0, s29, 0xe000
	s_nop 0
	global_load_lds_dwordx4 v[146:147], off
	s_waitcnt vmcnt(8)
	s_waitcnt lgkmcnt(0)
	s_barrier
	s_setprio 1
	v_mfma_i32_16x16x64_i8 v[126:129], v[142:145], v[200:203], v[126:129]
	v_mfma_i32_16x16x64_i8 v[118:121], v[172:175], v[200:203], v[118:121]
	v_mfma_i32_16x16x64_i8 v[110:113], v[142:145], v[208:211], v[110:113]
	v_mfma_i32_16x16x64_i8 v[102:105], v[172:175], v[208:211], v[102:105]
	v_mfma_i32_16x16x64_i8 v[94:97], v[142:145], v[216:219], v[94:97]
	v_mfma_i32_16x16x64_i8 v[86:89], v[172:175], v[216:219], v[86:89]
	v_mfma_i32_16x16x64_i8 v[78:81], v[142:145], v[224:227], v[78:81]
	v_mfma_i32_16x16x64_i8 v[70:73], v[172:175], v[224:227], v[70:73]
	v_mfma_i32_16x16x64_i8 v[126:129], v[168:171], v[204:207], v[126:129]
	v_mfma_i32_16x16x64_i8 v[118:121], v[180:183], v[204:207], v[118:121]
	v_mfma_i32_16x16x64_i8 v[110:113], v[168:171], v[212:215], v[110:113]
	v_mfma_i32_16x16x64_i8 v[102:105], v[180:183], v[212:215], v[102:105]
	v_mfma_i32_16x16x64_i8 v[94:97], v[168:171], v[220:223], v[94:97]
	v_mfma_i32_16x16x64_i8 v[86:89], v[180:183], v[220:223], v[86:89]
	v_mfma_i32_16x16x64_i8 v[78:81], v[168:171], v[228:231], v[78:81]
	v_mfma_i32_16x16x64_i8 v[70:73], v[180:183], v[228:231], v[70:73]
	s_setprio 0
	s_setprio 1
	v_mfma_i32_16x16x64_i8 v[122:125], v[184:187], v[200:203], v[122:125]
	v_mfma_i32_16x16x64_i8 v[114:117], v[192:195], v[200:203], v[114:117]
	v_mfma_i32_16x16x64_i8 v[106:109], v[184:187], v[208:211], v[106:109]
	v_mfma_i32_16x16x64_i8 v[98:101], v[192:195], v[208:211], v[98:101]
	v_mfma_i32_16x16x64_i8 v[90:93], v[184:187], v[216:219], v[90:93]
	v_mfma_i32_16x16x64_i8 v[82:85], v[192:195], v[216:219], v[82:85]
	v_mfma_i32_16x16x64_i8 v[74:77], v[184:187], v[224:227], v[74:77]
	v_mfma_i32_16x16x64_i8 v[66:69], v[192:195], v[224:227], v[66:69]
	v_mfma_i32_16x16x64_i8 v[122:125], v[188:191], v[204:207], v[122:125]
	v_mfma_i32_16x16x64_i8 v[114:117], v[196:199], v[204:207], v[114:117]
	v_mfma_i32_16x16x64_i8 v[106:109], v[188:191], v[212:215], v[106:109]
	v_mfma_i32_16x16x64_i8 v[98:101], v[196:199], v[212:215], v[98:101]
	v_mfma_i32_16x16x64_i8 v[90:93], v[188:191], v[220:223], v[90:93]
	v_mfma_i32_16x16x64_i8 v[82:85], v[196:199], v[220:223], v[82:85]
	v_mfma_i32_16x16x64_i8 v[74:77], v[188:191], v[228:231], v[74:77]
	v_mfma_i32_16x16x64_i8 v[66:69], v[196:199], v[228:231], v[66:69]
	s_setprio 0
	s_barrier
	s_add_i32 s71, s58, s45
	v_lshl_add_u64 v[146:147], s[34:35], 0, v[132:133]
	s_mov_b32 m0, s71
	ds_read_b128 v[200:203], v165 offset:16384
	ds_read_b128 v[204:207], v165 offset:17408
	ds_read_b128 v[208:211], v165 offset:18432
	ds_read_b128 v[212:215], v165 offset:19456
	ds_read_b128 v[216:219], v165 offset:20480
	ds_read_b128 v[220:223], v165 offset:21504
	ds_read_b128 v[224:227], v165 offset:22528
	ds_read_b128 v[228:231], v165 offset:23552
	global_load_lds_dwordx4 v[146:147], off
	s_add_i32 m0, s71, 0x2000
	s_add_u32 s72, s34, 0x80000
	v_lshl_add_u64 v[156:157], s[34:35], 0, v[136:137]
	s_addc_u32 s73, s35, 0
	s_add_i32 s71, s59, s45
	global_load_lds_dwordx4 v[156:157], off
	v_lshl_add_u64 v[176:177], s[72:73], 0, v[132:133]
	s_mov_b32 m0, s71
	v_lshl_add_u64 v[232:233], s[38:39], 0, v[134:135]
	global_load_lds_dwordx4 v[176:177], off
	v_lshl_add_u64 v[176:177], s[72:73], 0, v[136:137]
	s_add_i32 m0, s71, 0x2000
	s_nop 0
	global_load_lds_dwordx4 v[176:177], off
	v_lshl_add_u64 v[176:177], s[38:39], 0, v[130:131]
	s_mov_b32 m0, s29
	s_nop 0
	global_load_lds_dwordx4 v[176:177], off
	s_mov_b32 m0, s46
	s_nop 0
	global_load_lds_dwordx4 v[232:233], off
	s_waitcnt vmcnt(8)
	s_waitcnt lgkmcnt(0)
	s_barrier
	s_setprio 1
	v_mfma_i32_16x16x64_i8 v[62:65], v[142:145], v[200:203], v[62:65]
	v_mfma_i32_16x16x64_i8 v[54:57], v[172:175], v[200:203], v[54:57]
	v_mfma_i32_16x16x64_i8 v[46:49], v[142:145], v[208:211], v[46:49]
	v_mfma_i32_16x16x64_i8 v[38:41], v[172:175], v[208:211], v[38:41]
	v_mfma_i32_16x16x64_i8 v[30:33], v[142:145], v[216:219], v[30:33]
	v_mfma_i32_16x16x64_i8 v[22:25], v[172:175], v[216:219], v[22:25]
	v_mfma_i32_16x16x64_i8 v[14:17], v[142:145], v[224:227], v[14:17]
	v_mfma_i32_16x16x64_i8 v[6:9], v[172:175], v[224:227], v[6:9]
	v_mfma_i32_16x16x64_i8 v[62:65], v[168:171], v[204:207], v[62:65]
	v_mfma_i32_16x16x64_i8 v[54:57], v[180:183], v[204:207], v[54:57]
	v_mfma_i32_16x16x64_i8 v[46:49], v[168:171], v[212:215], v[46:49]
	v_mfma_i32_16x16x64_i8 v[38:41], v[180:183], v[212:215], v[38:41]
	v_mfma_i32_16x16x64_i8 v[30:33], v[168:171], v[220:223], v[30:33]
	v_mfma_i32_16x16x64_i8 v[22:25], v[180:183], v[220:223], v[22:25]
	v_mfma_i32_16x16x64_i8 v[14:17], v[168:171], v[228:231], v[14:17]
	v_mfma_i32_16x16x64_i8 v[6:9], v[180:183], v[228:231], v[6:9]
	s_setprio 0
	s_setprio 1
	v_mfma_i32_16x16x64_i8 v[58:61], v[184:187], v[200:203], v[58:61]
	v_mfma_i32_16x16x64_i8 v[50:53], v[192:195], v[200:203], v[50:53]
	v_mfma_i32_16x16x64_i8 v[42:45], v[184:187], v[208:211], v[42:45]
	v_mfma_i32_16x16x64_i8 v[34:37], v[192:195], v[208:211], v[34:37]
	v_mfma_i32_16x16x64_i8 v[26:29], v[184:187], v[216:219], v[26:29]
	v_mfma_i32_16x16x64_i8 v[18:21], v[192:195], v[216:219], v[18:21]
	v_mfma_i32_16x16x64_i8 v[10:13], v[184:187], v[224:227], v[10:13]
	v_mfma_i32_16x16x64_i8 v[2:5], v[192:195], v[224:227], v[2:5]
	v_mfma_i32_16x16x64_i8 v[58:61], v[188:191], v[204:207], v[58:61]
	v_mfma_i32_16x16x64_i8 v[50:53], v[196:199], v[204:207], v[50:53]
	v_mfma_i32_16x16x64_i8 v[42:45], v[188:191], v[212:215], v[42:45]
	v_mfma_i32_16x16x64_i8 v[34:37], v[196:199], v[212:215], v[34:37]
	v_mfma_i32_16x16x64_i8 v[26:29], v[188:191], v[220:223], v[26:29]
	v_mfma_i32_16x16x64_i8 v[18:21], v[196:199], v[220:223], v[18:21]
	v_mfma_i32_16x16x64_i8 v[10:13], v[188:191], v[228:231], v[10:13]
	v_mfma_i32_16x16x64_i8 v[2:5], v[196:199], v[228:231], v[2:5]
	s_setprio 0
	s_barrier
	s_add_i32 s71, 0, 0x18000
	v_add_u32_e32 v148, s71, v158
	s_add_i32 s72, 0, 0x1c000
	ds_read_b128 v[142:145], v148
	ds_read_b128 v[168:171], v148 offset:1024
	ds_read_b128 v[172:175], v148 offset:2048
	ds_read_b128 v[180:183], v148 offset:3072
	v_add_u32_e32 v148, s72, v158
	ds_read_b128 v[184:187], v148
	ds_read_b128 v[188:191], v148 offset:1024
	ds_read_b128 v[192:195], v148 offset:2048
	ds_read_b128 v[196:199], v148 offset:3072
	s_add_u32 s38, s38, 0x80000
	s_addc_u32 s39, s39, 0
	s_mov_b32 m0, s47
	v_lshl_add_u64 v[234:235], s[38:39], 0, v[130:131]
	ds_read_b128 v[200:203], v165 offset:32768
	ds_read_b128 v[204:207], v165 offset:33792
	ds_read_b128 v[208:211], v165 offset:34816
	ds_read_b128 v[212:215], v165 offset:35840
	ds_read_b128 v[216:219], v165 offset:36864
	ds_read_b128 v[220:223], v165 offset:37888
	ds_read_b128 v[224:227], v165 offset:38912
	ds_read_b128 v[228:231], v165 offset:39936
	global_load_lds_dwordx4 v[234:235], off
	v_lshl_add_u64 v[234:235], s[38:39], 0, v[134:135]
	s_mov_b32 m0, s48
	s_nop 0
	global_load_lds_dwordx4 v[234:235], off
	s_waitcnt vmcnt(8)
	s_waitcnt lgkmcnt(0)
	s_barrier
	s_setprio 1
	v_mfma_i32_16x16x64_i8 v[126:129], v[142:145], v[200:203], v[126:129]
	v_mfma_i32_16x16x64_i8 v[118:121], v[172:175], v[200:203], v[118:121]
	v_mfma_i32_16x16x64_i8 v[110:113], v[142:145], v[208:211], v[110:113]
	v_mfma_i32_16x16x64_i8 v[102:105], v[172:175], v[208:211], v[102:105]
	v_mfma_i32_16x16x64_i8 v[94:97], v[142:145], v[216:219], v[94:97]
	v_mfma_i32_16x16x64_i8 v[86:89], v[172:175], v[216:219], v[86:89]
	v_mfma_i32_16x16x64_i8 v[78:81], v[142:145], v[224:227], v[78:81]
	v_mfma_i32_16x16x64_i8 v[70:73], v[172:175], v[224:227], v[70:73]
	v_mfma_i32_16x16x64_i8 v[126:129], v[168:171], v[204:207], v[126:129]
	v_mfma_i32_16x16x64_i8 v[118:121], v[180:183], v[204:207], v[118:121]
	v_mfma_i32_16x16x64_i8 v[110:113], v[168:171], v[212:215], v[110:113]
	v_mfma_i32_16x16x64_i8 v[102:105], v[180:183], v[212:215], v[102:105]
	v_mfma_i32_16x16x64_i8 v[94:97], v[168:171], v[220:223], v[94:97]
	v_mfma_i32_16x16x64_i8 v[86:89], v[180:183], v[220:223], v[86:89]
	v_mfma_i32_16x16x64_i8 v[78:81], v[168:171], v[228:231], v[78:81]
	v_mfma_i32_16x16x64_i8 v[70:73], v[180:183], v[228:231], v[70:73]
	s_setprio 0
	s_setprio 1
	v_mfma_i32_16x16x64_i8 v[122:125], v[184:187], v[200:203], v[122:125]
	v_mfma_i32_16x16x64_i8 v[114:117], v[192:195], v[200:203], v[114:117]
	v_mfma_i32_16x16x64_i8 v[106:109], v[184:187], v[208:211], v[106:109]
	v_mfma_i32_16x16x64_i8 v[98:101], v[192:195], v[208:211], v[98:101]
	v_mfma_i32_16x16x64_i8 v[90:93], v[184:187], v[216:219], v[90:93]
	v_mfma_i32_16x16x64_i8 v[82:85], v[192:195], v[216:219], v[82:85]
	v_mfma_i32_16x16x64_i8 v[74:77], v[184:187], v[224:227], v[74:77]
	v_mfma_i32_16x16x64_i8 v[66:69], v[192:195], v[224:227], v[66:69]
	v_mfma_i32_16x16x64_i8 v[122:125], v[188:191], v[204:207], v[122:125]
	v_mfma_i32_16x16x64_i8 v[114:117], v[196:199], v[204:207], v[114:117]
	v_mfma_i32_16x16x64_i8 v[106:109], v[188:191], v[212:215], v[106:109]
	v_mfma_i32_16x16x64_i8 v[98:101], v[196:199], v[212:215], v[98:101]
	v_mfma_i32_16x16x64_i8 v[90:93], v[188:191], v[220:223], v[90:93]
	v_mfma_i32_16x16x64_i8 v[82:85], v[196:199], v[220:223], v[82:85]
	v_mfma_i32_16x16x64_i8 v[74:77], v[188:191], v[228:231], v[74:77]
	v_mfma_i32_16x16x64_i8 v[66:69], v[196:199], v[228:231], v[66:69]
	s_setprio 0
	s_barrier
	s_add_i32 s38, s71, s45
	v_lshl_add_u64 v[146:147], v[146:147], 0, s[8:9]
	s_mov_b32 m0, s38
	ds_read_b128 v[200:203], v165 offset:49152
	ds_read_b128 v[204:207], v165 offset:50176
	ds_read_b128 v[208:211], v165 offset:51200
	ds_read_b128 v[212:215], v165 offset:52224
	ds_read_b128 v[216:219], v165 offset:53248
	ds_read_b128 v[220:223], v165 offset:54272
	ds_read_b128 v[224:227], v165 offset:55296
	ds_read_b128 v[228:231], v165 offset:56320
	global_load_lds_dwordx4 v[146:147], off
	s_add_i32 m0, s38, 0x2000
	s_add_u32 s34, s34, 0x80080
	v_lshl_add_u64 v[146:147], v[156:157], 0, s[8:9]
	s_addc_u32 s35, s35, 0
	s_add_i32 s38, s72, s45
	global_load_lds_dwordx4 v[146:147], off
	v_lshl_add_u64 v[146:147], s[34:35], 0, v[132:133]
	s_mov_b32 m0, s38
	s_nop 0
	global_load_lds_dwordx4 v[146:147], off
	v_lshl_add_u64 v[146:147], s[34:35], 0, v[136:137]
	s_add_i32 m0, s38, 0x2000
	s_nop 0
	global_load_lds_dwordx4 v[146:147], off
	v_lshl_add_u64 v[146:147], v[176:177], 0, s[8:9]
	s_mov_b32 m0, s52
	s_nop 0
	global_load_lds_dwordx4 v[146:147], off
	v_lshl_add_u64 v[146:147], v[232:233], 0, s[8:9]
	s_mov_b32 m0, s53
	s_nop 0
	global_load_lds_dwordx4 v[146:147], off
	s_waitcnt vmcnt(8)
	s_waitcnt lgkmcnt(0)
	s_barrier
	s_setprio 1
	v_mfma_i32_16x16x64_i8 v[62:65], v[142:145], v[200:203], v[62:65]
	v_mfma_i32_16x16x64_i8 v[54:57], v[172:175], v[200:203], v[54:57]
	v_mfma_i32_16x16x64_i8 v[46:49], v[142:145], v[208:211], v[46:49]
	v_mfma_i32_16x16x64_i8 v[38:41], v[172:175], v[208:211], v[38:41]
	v_mfma_i32_16x16x64_i8 v[30:33], v[142:145], v[216:219], v[30:33]
	v_mfma_i32_16x16x64_i8 v[22:25], v[172:175], v[216:219], v[22:25]
	v_mfma_i32_16x16x64_i8 v[14:17], v[142:145], v[224:227], v[14:17]
	v_mfma_i32_16x16x64_i8 v[6:9], v[172:175], v[224:227], v[6:9]
	v_mfma_i32_16x16x64_i8 v[62:65], v[168:171], v[204:207], v[62:65]
	v_mfma_i32_16x16x64_i8 v[54:57], v[180:183], v[204:207], v[54:57]
	v_mfma_i32_16x16x64_i8 v[46:49], v[168:171], v[212:215], v[46:49]
	v_mfma_i32_16x16x64_i8 v[38:41], v[180:183], v[212:215], v[38:41]
	v_mfma_i32_16x16x64_i8 v[30:33], v[168:171], v[220:223], v[30:33]
	v_mfma_i32_16x16x64_i8 v[22:25], v[180:183], v[220:223], v[22:25]
	v_mfma_i32_16x16x64_i8 v[14:17], v[168:171], v[228:231], v[14:17]
	v_mfma_i32_16x16x64_i8 v[6:9], v[180:183], v[228:231], v[6:9]
	s_setprio 0
	s_setprio 1
	v_mfma_i32_16x16x64_i8 v[58:61], v[184:187], v[200:203], v[58:61]
	v_mfma_i32_16x16x64_i8 v[50:53], v[192:195], v[200:203], v[50:53]
	v_mfma_i32_16x16x64_i8 v[42:45], v[184:187], v[208:211], v[42:45]
	v_mfma_i32_16x16x64_i8 v[34:37], v[192:195], v[208:211], v[34:37]
	v_mfma_i32_16x16x64_i8 v[26:29], v[184:187], v[216:219], v[26:29]
	v_mfma_i32_16x16x64_i8 v[18:21], v[192:195], v[216:219], v[18:21]
	v_mfma_i32_16x16x64_i8 v[10:13], v[184:187], v[224:227], v[10:13]
	v_mfma_i32_16x16x64_i8 v[2:5], v[192:195], v[224:227], v[2:5]
	v_mfma_i32_16x16x64_i8 v[58:61], v[188:191], v[204:207], v[58:61]
	v_mfma_i32_16x16x64_i8 v[50:53], v[196:199], v[204:207], v[50:53]
	v_mfma_i32_16x16x64_i8 v[42:45], v[188:191], v[212:215], v[42:45]
	v_mfma_i32_16x16x64_i8 v[34:37], v[196:199], v[212:215], v[34:37]
	v_mfma_i32_16x16x64_i8 v[26:29], v[188:191], v[220:223], v[26:29]
	v_mfma_i32_16x16x64_i8 v[18:21], v[196:199], v[220:223], v[18:21]
	v_mfma_i32_16x16x64_i8 v[10:13], v[188:191], v[228:231], v[10:13]
	v_mfma_i32_16x16x64_i8 v[2:5], v[196:199], v[228:231], v[2:5]
	s_setprio 0
	s_barrier
	s_add_i32 s70, s70, 2
	s_add_u32 s30, s30, 0x100
	s_addc_u32 s31, s31, 0
	s_add_u32 s68, s68, 0x100
	s_addc_u32 s69, s69, 0
	s_cmp_gt_u32 s70, 29
	s_cbranch_scc0 .LBB0_1638
	s_and_b64 vcc, exec, s[10:11]
	s_cbranch_vccz .LBB0_1641
	s_barrier

.LBB0_1657:
	ds_read_b128 v[146:149], v165
	ds_read_b128 v[170:173], v165 offset:1024
	ds_read_b128 v[174:177], v165 offset:2048
	ds_read_b128 v[180:183], v165 offset:3072
	ds_read_b128 v[184:187], v167
	ds_read_b128 v[188:191], v167 offset:1024
	ds_read_b128 v[192:195], v167 offset:2048
	ds_read_b128 v[196:199], v167 offset:3072
	s_add_u32 s30, s28, 0xfff80080
	s_addc_u32 s31, s29, -1
	s_cmp_eq_u32 s68, 28
	s_cselect_b32 s35, s19, s31
	s_cselect_b32 s34, s27, s30
	s_cselect_b32 s31, s17, s67
	s_cselect_b32 s30, s65, s66
	v_lshl_add_u64 v[150:151], s[28:29], 0, v[138:139]
	s_add_i32 m0, s45, 0xc000
	ds_read_b128 v[200:203], v168
	ds_read_b128 v[204:207], v168 offset:1024
	ds_read_b128 v[208:211], v168 offset:2048
	ds_read_b128 v[212:215], v168 offset:3072
	ds_read_b128 v[216:219], v168 offset:4096
	ds_read_b128 v[220:223], v168 offset:5120
	ds_read_b128 v[224:227], v168 offset:6144
	ds_read_b128 v[228:231], v168 offset:7168
	global_load_lds_dwordx4 v[150:151], off
	v_lshl_add_u64 v[150:151], s[28:29], 0, v[140:141]
	s_add_i32 m0, s45, 0xe000
	s_nop 0
	global_load_lds_dwordx4 v[150:151], off
	s_waitcnt vmcnt(8)
	s_waitcnt lgkmcnt(0)
	s_barrier
	s_setprio 1
	v_mfma_i32_16x16x64_i8 v[126:129], v[146:149], v[200:203], v[126:129]
	v_mfma_i32_16x16x64_i8 v[118:121], v[174:177], v[200:203], v[118:121]
	v_mfma_i32_16x16x64_i8 v[110:113], v[146:149], v[208:211], v[110:113]
	v_mfma_i32_16x16x64_i8 v[102:105], v[174:177], v[208:211], v[102:105]
	v_mfma_i32_16x16x64_i8 v[94:97], v[146:149], v[216:219], v[94:97]
	v_mfma_i32_16x16x64_i8 v[86:89], v[174:177], v[216:219], v[86:89]
	v_mfma_i32_16x16x64_i8 v[78:81], v[146:149], v[224:227], v[78:81]
	v_mfma_i32_16x16x64_i8 v[70:73], v[174:177], v[224:227], v[70:73]
	v_mfma_i32_16x16x64_i8 v[126:129], v[170:173], v[204:207], v[126:129]
	v_mfma_i32_16x16x64_i8 v[118:121], v[180:183], v[204:207], v[118:121]
	v_mfma_i32_16x16x64_i8 v[110:113], v[170:173], v[212:215], v[110:113]
	v_mfma_i32_16x16x64_i8 v[102:105], v[180:183], v[212:215], v[102:105]
	v_mfma_i32_16x16x64_i8 v[94:97], v[170:173], v[220:223], v[94:97]
	v_mfma_i32_16x16x64_i8 v[86:89], v[180:183], v[220:223], v[86:89]
	v_mfma_i32_16x16x64_i8 v[78:81], v[170:173], v[228:231], v[78:81]
	v_mfma_i32_16x16x64_i8 v[70:73], v[180:183], v[228:231], v[70:73]
	s_setprio 0
	s_setprio 1
	v_mfma_i32_16x16x64_i8 v[122:125], v[184:187], v[200:203], v[122:125]
	v_mfma_i32_16x16x64_i8 v[114:117], v[192:195], v[200:203], v[114:117]
	v_mfma_i32_16x16x64_i8 v[106:109], v[184:187], v[208:211], v[106:109]
	v_mfma_i32_16x16x64_i8 v[98:101], v[192:195], v[208:211], v[98:101]
	v_mfma_i32_16x16x64_i8 v[90:93], v[184:187], v[216:219], v[90:93]
	v_mfma_i32_16x16x64_i8 v[82:85], v[192:195], v[216:219], v[82:85]
	v_mfma_i32_16x16x64_i8 v[74:77], v[184:187], v[224:227], v[74:77]
	v_mfma_i32_16x16x64_i8 v[66:69], v[192:195], v[224:227], v[66:69]
	v_mfma_i32_16x16x64_i8 v[122:125], v[188:191], v[204:207], v[122:125]
	v_mfma_i32_16x16x64_i8 v[114:117], v[196:199], v[204:207], v[114:117]
	v_mfma_i32_16x16x64_i8 v[106:109], v[188:191], v[212:215], v[106:109]
	v_mfma_i32_16x16x64_i8 v[98:101], v[196:199], v[212:215], v[98:101]
	v_mfma_i32_16x16x64_i8 v[90:93], v[188:191], v[220:223], v[90:93]
	v_mfma_i32_16x16x64_i8 v[82:85], v[196:199], v[220:223], v[82:85]
	v_mfma_i32_16x16x64_i8 v[74:77], v[188:191], v[228:231], v[74:77]
	v_mfma_i32_16x16x64_i8 v[66:69], v[196:199], v[228:231], v[66:69]
	s_setprio 0
	s_barrier
	s_add_i32 s69, s55, s15
	v_lshl_add_u64 v[150:151], s[30:31], 0, v[132:133]
	s_mov_b32 m0, s69
	ds_read_b128 v[200:203], v168 offset:16384
	ds_read_b128 v[204:207], v168 offset:17408
	ds_read_b128 v[208:211], v168 offset:18432
	ds_read_b128 v[212:215], v168 offset:19456
	ds_read_b128 v[216:219], v168 offset:20480
	ds_read_b128 v[220:223], v168 offset:21504
	ds_read_b128 v[224:227], v168 offset:22528
	ds_read_b128 v[228:231], v168 offset:23552
	global_load_lds_dwordx4 v[150:151], off
	s_add_i32 m0, s69, 0x2000
	s_add_u32 s70, s30, 0x80000
	v_lshl_add_u64 v[160:161], s[30:31], 0, v[136:137]
	s_addc_u32 s71, s31, 0
	s_add_i32 s69, s56, s15
	global_load_lds_dwordx4 v[160:161], off
	v_lshl_add_u64 v[232:233], s[70:71], 0, v[132:133]
	s_mov_b32 m0, s69
	v_lshl_add_u64 v[234:235], s[34:35], 0, v[134:135]
	global_load_lds_dwordx4 v[232:233], off
	v_lshl_add_u64 v[232:233], s[70:71], 0, v[136:137]
	s_add_i32 m0, s69, 0x2000
	s_nop 0
	global_load_lds_dwordx4 v[232:233], off
	v_lshl_add_u64 v[232:233], s[34:35], 0, v[130:131]
	s_mov_b32 m0, s45
	s_nop 0
	global_load_lds_dwordx4 v[232:233], off
	s_mov_b32 m0, s46
	s_nop 0
	global_load_lds_dwordx4 v[234:235], off
	s_waitcnt vmcnt(8)
	s_waitcnt lgkmcnt(0)
	s_barrier
	s_setprio 1
	v_mfma_i32_16x16x64_i8 v[62:65], v[146:149], v[200:203], v[62:65]
	v_mfma_i32_16x16x64_i8 v[54:57], v[174:177], v[200:203], v[54:57]
	v_mfma_i32_16x16x64_i8 v[46:49], v[146:149], v[208:211], v[46:49]
	v_mfma_i32_16x16x64_i8 v[38:41], v[174:177], v[208:211], v[38:41]
	v_mfma_i32_16x16x64_i8 v[30:33], v[146:149], v[216:219], v[30:33]
	v_mfma_i32_16x16x64_i8 v[22:25], v[174:177], v[216:219], v[22:25]
	v_mfma_i32_16x16x64_i8 v[14:17], v[146:149], v[224:227], v[14:17]
	v_mfma_i32_16x16x64_i8 v[6:9], v[174:177], v[224:227], v[6:9]
	v_mfma_i32_16x16x64_i8 v[62:65], v[170:173], v[204:207], v[62:65]
	v_mfma_i32_16x16x64_i8 v[54:57], v[180:183], v[204:207], v[54:57]
	v_mfma_i32_16x16x64_i8 v[46:49], v[170:173], v[212:215], v[46:49]
	v_mfma_i32_16x16x64_i8 v[38:41], v[180:183], v[212:215], v[38:41]
	v_mfma_i32_16x16x64_i8 v[30:33], v[170:173], v[220:223], v[30:33]
	v_mfma_i32_16x16x64_i8 v[22:25], v[180:183], v[220:223], v[22:25]
	v_mfma_i32_16x16x64_i8 v[14:17], v[170:173], v[228:231], v[14:17]
	v_mfma_i32_16x16x64_i8 v[6:9], v[180:183], v[228:231], v[6:9]
	s_setprio 0
	s_setprio 1
	v_mfma_i32_16x16x64_i8 v[58:61], v[184:187], v[200:203], v[58:61]
	v_mfma_i32_16x16x64_i8 v[50:53], v[192:195], v[200:203], v[50:53]
	v_mfma_i32_16x16x64_i8 v[42:45], v[184:187], v[208:211], v[42:45]
	v_mfma_i32_16x16x64_i8 v[34:37], v[192:195], v[208:211], v[34:37]
	v_mfma_i32_16x16x64_i8 v[26:29], v[184:187], v[216:219], v[26:29]
	v_mfma_i32_16x16x64_i8 v[18:21], v[192:195], v[216:219], v[18:21]
	v_mfma_i32_16x16x64_i8 v[10:13], v[184:187], v[224:227], v[10:13]
	v_mfma_i32_16x16x64_i8 v[2:5], v[192:195], v[224:227], v[2:5]
	v_mfma_i32_16x16x64_i8 v[58:61], v[188:191], v[204:207], v[58:61]
	v_mfma_i32_16x16x64_i8 v[50:53], v[196:199], v[204:207], v[50:53]
	v_mfma_i32_16x16x64_i8 v[42:45], v[188:191], v[212:215], v[42:45]
	v_mfma_i32_16x16x64_i8 v[34:37], v[196:199], v[212:215], v[34:37]
	v_mfma_i32_16x16x64_i8 v[26:29], v[188:191], v[220:223], v[26:29]
	v_mfma_i32_16x16x64_i8 v[18:21], v[196:199], v[220:223], v[18:21]
	v_mfma_i32_16x16x64_i8 v[10:13], v[188:191], v[228:231], v[10:13]
	v_mfma_i32_16x16x64_i8 v[2:5], v[196:199], v[228:231], v[2:5]
	s_setprio 0
	s_barrier
	s_add_i32 s69, 0, 0x18000
	v_add_u32_e32 v152, s69, v157
	s_add_i32 s70, 0, 0x1c000
	ds_read_b128 v[146:149], v152
	ds_read_b128 v[170:173], v152 offset:1024
	ds_read_b128 v[174:177], v152 offset:2048
	ds_read_b128 v[180:183], v152 offset:3072
	v_add_u32_e32 v152, s70, v157
	ds_read_b128 v[184:187], v152
	ds_read_b128 v[188:191], v152 offset:1024
	ds_read_b128 v[192:195], v152 offset:2048
	ds_read_b128 v[196:199], v152 offset:3072
	s_add_u32 s34, s34, 0x80000
	s_addc_u32 s35, s35, 0
	s_mov_b32 m0, s47
	v_lshl_add_u64 v[236:237], s[34:35], 0, v[130:131]
	ds_read_b128 v[200:203], v168 offset:32768
	ds_read_b128 v[204:207], v168 offset:33792
	ds_read_b128 v[208:211], v168 offset:34816
	ds_read_b128 v[212:215], v168 offset:35840
	ds_read_b128 v[216:219], v168 offset:36864
	ds_read_b128 v[220:223], v168 offset:37888
	ds_read_b128 v[224:227], v168 offset:38912
	ds_read_b128 v[228:231], v168 offset:39936
	global_load_lds_dwordx4 v[236:237], off
	v_lshl_add_u64 v[236:237], s[34:35], 0, v[134:135]
	s_mov_b32 m0, s48
	s_nop 0
	global_load_lds_dwordx4 v[236:237], off
	s_waitcnt vmcnt(8)
	s_waitcnt lgkmcnt(0)
	s_barrier
	s_setprio 1
	v_mfma_i32_16x16x64_i8 v[126:129], v[146:149], v[200:203], v[126:129]
	v_mfma_i32_16x16x64_i8 v[118:121], v[174:177], v[200:203], v[118:121]
	v_mfma_i32_16x16x64_i8 v[110:113], v[146:149], v[208:211], v[110:113]
	v_mfma_i32_16x16x64_i8 v[102:105], v[174:177], v[208:211], v[102:105]
	v_mfma_i32_16x16x64_i8 v[94:97], v[146:149], v[216:219], v[94:97]
	v_mfma_i32_16x16x64_i8 v[86:89], v[174:177], v[216:219], v[86:89]
	v_mfma_i32_16x16x64_i8 v[78:81], v[146:149], v[224:227], v[78:81]
	v_mfma_i32_16x16x64_i8 v[70:73], v[174:177], v[224:227], v[70:73]
	v_mfma_i32_16x16x64_i8 v[126:129], v[170:173], v[204:207], v[126:129]
	v_mfma_i32_16x16x64_i8 v[118:121], v[180:183], v[204:207], v[118:121]
	v_mfma_i32_16x16x64_i8 v[110:113], v[170:173], v[212:215], v[110:113]
	v_mfma_i32_16x16x64_i8 v[102:105], v[180:183], v[212:215], v[102:105]
	v_mfma_i32_16x16x64_i8 v[94:97], v[170:173], v[220:223], v[94:97]
	v_mfma_i32_16x16x64_i8 v[86:89], v[180:183], v[220:223], v[86:89]
	v_mfma_i32_16x16x64_i8 v[78:81], v[170:173], v[228:231], v[78:81]
	v_mfma_i32_16x16x64_i8 v[70:73], v[180:183], v[228:231], v[70:73]
	s_setprio 0
	s_setprio 1
	v_mfma_i32_16x16x64_i8 v[122:125], v[184:187], v[200:203], v[122:125]
	v_mfma_i32_16x16x64_i8 v[114:117], v[192:195], v[200:203], v[114:117]
	v_mfma_i32_16x16x64_i8 v[106:109], v[184:187], v[208:211], v[106:109]
	v_mfma_i32_16x16x64_i8 v[98:101], v[192:195], v[208:211], v[98:101]
	v_mfma_i32_16x16x64_i8 v[90:93], v[184:187], v[216:219], v[90:93]
	v_mfma_i32_16x16x64_i8 v[82:85], v[192:195], v[216:219], v[82:85]
	v_mfma_i32_16x16x64_i8 v[74:77], v[184:187], v[224:227], v[74:77]
	v_mfma_i32_16x16x64_i8 v[66:69], v[192:195], v[224:227], v[66:69]
	v_mfma_i32_16x16x64_i8 v[122:125], v[188:191], v[204:207], v[122:125]
	v_mfma_i32_16x16x64_i8 v[114:117], v[196:199], v[204:207], v[114:117]
	v_mfma_i32_16x16x64_i8 v[106:109], v[188:191], v[212:215], v[106:109]
	v_mfma_i32_16x16x64_i8 v[98:101], v[196:199], v[212:215], v[98:101]
	v_mfma_i32_16x16x64_i8 v[90:93], v[188:191], v[220:223], v[90:93]
	v_mfma_i32_16x16x64_i8 v[82:85], v[196:199], v[220:223], v[82:85]
	v_mfma_i32_16x16x64_i8 v[74:77], v[188:191], v[228:231], v[74:77]
	v_mfma_i32_16x16x64_i8 v[66:69], v[196:199], v[228:231], v[66:69]
	s_setprio 0
	s_barrier
	s_add_i32 s34, s69, s15
	v_lshl_add_u64 v[150:151], v[150:151], 0, s[10:11]
	s_mov_b32 m0, s34
	ds_read_b128 v[200:203], v168 offset:49152
	ds_read_b128 v[204:207], v168 offset:50176
	ds_read_b128 v[208:211], v168 offset:51200
	ds_read_b128 v[212:215], v168 offset:52224
	ds_read_b128 v[216:219], v168 offset:53248
	ds_read_b128 v[220:223], v168 offset:54272
	ds_read_b128 v[224:227], v168 offset:55296
	ds_read_b128 v[228:231], v168 offset:56320
	global_load_lds_dwordx4 v[150:151], off
	s_add_i32 m0, s34, 0x2000
	s_add_u32 s30, s30, 0x80080
	v_lshl_add_u64 v[150:151], v[160:161], 0, s[10:11]
	s_addc_u32 s31, s31, 0
	s_add_i32 s34, s70, s15
	global_load_lds_dwordx4 v[150:151], off
	v_lshl_add_u64 v[150:151], s[30:31], 0, v[132:133]
	s_mov_b32 m0, s34
	s_nop 0
	global_load_lds_dwordx4 v[150:151], off
	v_lshl_add_u64 v[150:151], s[30:31], 0, v[136:137]
	s_add_i32 m0, s34, 0x2000
	s_nop 0
	global_load_lds_dwordx4 v[150:151], off
	v_lshl_add_u64 v[150:151], v[232:233], 0, s[10:11]
	s_mov_b32 m0, s52
	s_nop 0
	global_load_lds_dwordx4 v[150:151], off
	v_lshl_add_u64 v[150:151], v[234:235], 0, s[10:11]
	s_mov_b32 m0, s53
	s_nop 0
	global_load_lds_dwordx4 v[150:151], off
	s_waitcnt vmcnt(8)
	s_waitcnt lgkmcnt(0)
	s_barrier
	s_setprio 1
	v_mfma_i32_16x16x64_i8 v[62:65], v[146:149], v[200:203], v[62:65]
	v_mfma_i32_16x16x64_i8 v[54:57], v[174:177], v[200:203], v[54:57]
	v_mfma_i32_16x16x64_i8 v[46:49], v[146:149], v[208:211], v[46:49]
	v_mfma_i32_16x16x64_i8 v[38:41], v[174:177], v[208:211], v[38:41]
	v_mfma_i32_16x16x64_i8 v[30:33], v[146:149], v[216:219], v[30:33]
	v_mfma_i32_16x16x64_i8 v[22:25], v[174:177], v[216:219], v[22:25]
	v_mfma_i32_16x16x64_i8 v[14:17], v[146:149], v[224:227], v[14:17]
	v_mfma_i32_16x16x64_i8 v[6:9], v[174:177], v[224:227], v[6:9]
	v_mfma_i32_16x16x64_i8 v[62:65], v[170:173], v[204:207], v[62:65]
	v_mfma_i32_16x16x64_i8 v[54:57], v[180:183], v[204:207], v[54:57]
	v_mfma_i32_16x16x64_i8 v[46:49], v[170:173], v[212:215], v[46:49]
	v_mfma_i32_16x16x64_i8 v[38:41], v[180:183], v[212:215], v[38:41]
	v_mfma_i32_16x16x64_i8 v[30:33], v[170:173], v[220:223], v[30:33]
	v_mfma_i32_16x16x64_i8 v[22:25], v[180:183], v[220:223], v[22:25]
	v_mfma_i32_16x16x64_i8 v[14:17], v[170:173], v[228:231], v[14:17]
	v_mfma_i32_16x16x64_i8 v[6:9], v[180:183], v[228:231], v[6:9]
	s_setprio 0
	s_setprio 1
	v_mfma_i32_16x16x64_i8 v[58:61], v[184:187], v[200:203], v[58:61]
	v_mfma_i32_16x16x64_i8 v[50:53], v[192:195], v[200:203], v[50:53]
	v_mfma_i32_16x16x64_i8 v[42:45], v[184:187], v[208:211], v[42:45]
	v_mfma_i32_16x16x64_i8 v[34:37], v[192:195], v[208:211], v[34:37]
	v_mfma_i32_16x16x64_i8 v[26:29], v[184:187], v[216:219], v[26:29]
	v_mfma_i32_16x16x64_i8 v[18:21], v[192:195], v[216:219], v[18:21]
	v_mfma_i32_16x16x64_i8 v[10:13], v[184:187], v[224:227], v[10:13]
	v_mfma_i32_16x16x64_i8 v[2:5], v[192:195], v[224:227], v[2:5]
	v_mfma_i32_16x16x64_i8 v[58:61], v[188:191], v[204:207], v[58:61]
	v_mfma_i32_16x16x64_i8 v[50:53], v[196:199], v[204:207], v[50:53]
	v_mfma_i32_16x16x64_i8 v[42:45], v[188:191], v[212:215], v[42:45]
	v_mfma_i32_16x16x64_i8 v[34:37], v[196:199], v[212:215], v[34:37]
	v_mfma_i32_16x16x64_i8 v[26:29], v[188:191], v[220:223], v[26:29]
	v_mfma_i32_16x16x64_i8 v[18:21], v[196:199], v[220:223], v[18:21]
	v_mfma_i32_16x16x64_i8 v[10:13], v[188:191], v[228:231], v[10:13]
	v_mfma_i32_16x16x64_i8 v[2:5], v[196:199], v[228:231], v[2:5]
	s_setprio 0
	s_barrier
	s_add_i32 s68, s68, 2
	s_add_u32 s28, s28, 0x100
	s_addc_u32 s29, s29, 0
	s_add_u32 s66, s66, 0x100
	s_addc_u32 s67, s67, 0
	s_cmp_gt_u32 s68, 29
	s_cbranch_scc0 .LBB0_1657
	s_and_b64 vcc, exec, s[12:13]
	s_cbranch_vccz .LBB0_1660
	s_barrier

.LBB0_1690:
	ds_read_b128 v[26:29], v181
	ds_read_b128 v[30:33], v181 offset:1024
	ds_read_b128 v[18:21], v181 offset:2048
	ds_read_b128 v[22:25], v181 offset:3072
	ds_read_b128 v[10:13], v182
	ds_read_b128 v[14:17], v182 offset:1024
	ds_read_b128 v[2:5], v182 offset:2048
	ds_read_b128 v[6:9], v182 offset:3072
	s_add_i32 s70, s42, 2
	s_add_u32 s43, s40, 0xffea8080
	s_addc_u32 s44, s41, -1
	s_cmp_eq_u32 s29, s42
	s_cselect_b32 s42, s34, s68
	s_cselect_b32 s45, s31, s44
	s_cselect_b32 s44, s30, s43
	s_cselect_b32 s43, s35, s69
	v_lshl_add_u64 v[208:209], s[40:41], 0, v[166:167]
	s_add_i32 m0, s48, 0xc000
	ds_read_b128 v[170:173], v183
	ds_read_b128 v[174:177], v183 offset:1024
	ds_read_b128 v[184:187], v183 offset:2048
	ds_read_b128 v[188:191], v183 offset:3072
	ds_read_b128 v[192:195], v183 offset:4096
	ds_read_b128 v[196:199], v183 offset:5120
	ds_read_b128 v[200:203], v183 offset:6144
	ds_read_b128 v[204:207], v183 offset:7168
	global_load_lds_dwordx4 v[208:209], off
	v_lshl_add_u64 v[208:209], s[40:41], 0, v[168:169]
	s_add_i32 m0, s48, 0xe000
	s_nop 0
	global_load_lds_dwordx4 v[208:209], off
	s_waitcnt vmcnt(8)
	s_waitcnt lgkmcnt(0)
	s_barrier
	s_setprio 1
	v_mfma_f32_16x16x128_f8f6f4 v[158:161], v[26:33], v[170:177], v[158:161]
	v_mfma_f32_16x16x128_f8f6f4 v[154:157], v[18:25], v[170:177], v[154:157]
	v_mfma_f32_16x16x128_f8f6f4 v[150:153], v[26:33], v[184:191], v[150:153]
	v_mfma_f32_16x16x128_f8f6f4 v[138:141], v[18:25], v[184:191], v[138:141]
	v_mfma_f32_16x16x128_f8f6f4 v[130:133], v[26:33], v[192:199], v[130:133]
	v_mfma_f32_16x16x128_f8f6f4 v[122:125], v[18:25], v[192:199], v[122:125]
	v_mfma_f32_16x16x128_f8f6f4 v[114:117], v[26:33], v[200:207], v[114:117]
	v_mfma_f32_16x16x128_f8f6f4 v[106:109], v[18:25], v[200:207], v[106:109]
	s_setprio 0
	s_setprio 1
	v_mfma_f32_16x16x128_f8f6f4 v[146:149], v[10:17], v[170:177], v[146:149]
	v_mfma_f32_16x16x128_f8f6f4 v[142:145], v[2:9], v[170:177], v[142:145]
	v_mfma_f32_16x16x128_f8f6f4 v[134:137], v[10:17], v[184:191], v[134:137]
	v_mfma_f32_16x16x128_f8f6f4 v[126:129], v[2:9], v[184:191], v[126:129]
	v_mfma_f32_16x16x128_f8f6f4 v[118:121], v[10:17], v[192:199], v[118:121]
	v_mfma_f32_16x16x128_f8f6f4 v[110:113], v[2:9], v[192:199], v[110:113]
	v_mfma_f32_16x16x128_f8f6f4 v[102:105], v[10:17], v[200:207], v[102:105]
	v_mfma_f32_16x16x128_f8f6f4 v[98:101], v[2:9], v[200:207], v[98:101]
	s_setprio 0
	s_barrier
	s_add_i32 s71, s60, s47
	v_lshl_add_u64 v[170:171], s[42:43], 0, v[164:165]
	s_mov_b32 m0, s71
	ds_read_b128 v[184:187], v183 offset:16384
	ds_read_b128 v[188:191], v183 offset:17408
	ds_read_b128 v[192:195], v183 offset:18432
	ds_read_b128 v[196:199], v183 offset:19456
	ds_read_b128 v[200:203], v183 offset:20480
	ds_read_b128 v[204:207], v183 offset:21504
	ds_read_b128 v[208:211], v183 offset:22528
	ds_read_b128 v[212:215], v183 offset:23552
	global_load_lds_dwordx4 v[170:171], off
	s_add_i32 m0, s71, 0x2000
	s_add_u32 s72, s42, 0x158000
	v_lshl_add_u64 v[172:173], s[42:43], 0, v[162:163]
	s_addc_u32 s73, s43, 0
	s_add_i32 s71, s61, s47
	global_load_lds_dwordx4 v[172:173], off
	v_lshl_add_u64 v[174:175], s[72:73], 0, v[164:165]
	s_mov_b32 m0, s71
	v_lshl_add_u64 v[176:177], s[44:45], 0, v[162:163]
	global_load_lds_dwordx4 v[174:175], off
	v_lshl_add_u64 v[174:175], s[72:73], 0, v[162:163]
	s_add_i32 m0, s71, 0x2000
	s_nop 0
	global_load_lds_dwordx4 v[174:175], off
	v_lshl_add_u64 v[174:175], s[44:45], 0, v[164:165]
	s_mov_b32 m0, s48
	s_nop 0
	global_load_lds_dwordx4 v[174:175], off
	s_mov_b32 m0, s49
	s_nop 0
	global_load_lds_dwordx4 v[176:177], off
	s_waitcnt vmcnt(8)
	s_waitcnt lgkmcnt(0)
	s_barrier
	s_setprio 1
	v_mfma_f32_16x16x128_f8f6f4 v[94:97], v[26:33], v[184:191], v[94:97]
	v_mfma_f32_16x16x128_f8f6f4 v[90:93], v[18:25], v[184:191], v[90:93]
	v_mfma_f32_16x16x128_f8f6f4 v[82:85], v[26:33], v[192:199], v[82:85]
	v_mfma_f32_16x16x128_f8f6f4 v[74:77], v[18:25], v[192:199], v[74:77]
	v_mfma_f32_16x16x128_f8f6f4 v[66:69], v[26:33], v[200:207], v[66:69]
	v_mfma_f32_16x16x128_f8f6f4 v[58:61], v[18:25], v[200:207], v[58:61]
	v_mfma_f32_16x16x128_f8f6f4 v[50:53], v[26:33], v[208:215], v[50:53]
	v_mfma_f32_16x16x128_f8f6f4 v[42:45], v[18:25], v[208:215], v[42:45]
	s_setprio 0
	s_setprio 1
	v_mfma_f32_16x16x128_f8f6f4 v[86:89], v[10:17], v[184:191], v[86:89]
	v_mfma_f32_16x16x128_f8f6f4 v[78:81], v[2:9], v[184:191], v[78:81]
	v_mfma_f32_16x16x128_f8f6f4 v[70:73], v[10:17], v[192:199], v[70:73]
	v_mfma_f32_16x16x128_f8f6f4 v[62:65], v[2:9], v[192:199], v[62:65]
	v_mfma_f32_16x16x128_f8f6f4 v[54:57], v[10:17], v[200:207], v[54:57]
	v_mfma_f32_16x16x128_f8f6f4 v[46:49], v[2:9], v[200:207], v[46:49]
	v_mfma_f32_16x16x128_f8f6f4 v[38:41], v[10:17], v[208:215], v[38:41]
	v_mfma_f32_16x16x128_f8f6f4 v[34:37], v[2:9], v[208:215], v[34:37]
	s_setprio 0
	s_barrier
	s_add_i32 s71, 0, 0x18000
	s_add_i32 s72, 0, 0x1c000
	v_add_u32_e32 v14, s71, v180
	v_add_u32_e32 v30, s72, v180
	ds_read_b128 v[2:5], v14
	ds_read_b128 v[6:9], v14 offset:1024
	ds_read_b128 v[10:13], v14 offset:2048
	ds_read_b128 v[14:17], v14 offset:3072
	ds_read_b128 v[18:21], v30
	ds_read_b128 v[22:25], v30 offset:1024
	ds_read_b128 v[26:29], v30 offset:2048
	ds_read_b128 v[30:33], v30 offset:3072
	s_add_u32 s44, s44, 0x158000
	s_addc_u32 s45, s45, 0
	s_mov_b32 m0, s50
	v_lshl_add_u64 v[216:217], s[44:45], 0, v[164:165]
	ds_read_b128 v[184:187], v183 offset:32768
	ds_read_b128 v[188:191], v183 offset:33792
	ds_read_b128 v[192:195], v183 offset:34816
	ds_read_b128 v[196:199], v183 offset:35840
	ds_read_b128 v[200:203], v183 offset:36864
	ds_read_b128 v[204:207], v183 offset:37888
	ds_read_b128 v[208:211], v183 offset:38912
	ds_read_b128 v[212:215], v183 offset:39936
	global_load_lds_dwordx4 v[216:217], off
	v_lshl_add_u64 v[216:217], s[44:45], 0, v[162:163]
	s_mov_b32 m0, s51
	s_nop 0
	global_load_lds_dwordx4 v[216:217], off
	s_waitcnt vmcnt(8)
	s_waitcnt lgkmcnt(0)
	s_barrier
	s_setprio 1
	v_mfma_f32_16x16x128_f8f6f4 v[158:161], v[2:9], v[184:191], v[158:161]
	v_mfma_f32_16x16x128_f8f6f4 v[154:157], v[10:17], v[184:191], v[154:157]
	v_mfma_f32_16x16x128_f8f6f4 v[150:153], v[2:9], v[192:199], v[150:153]
	v_mfma_f32_16x16x128_f8f6f4 v[138:141], v[10:17], v[192:199], v[138:141]
	v_mfma_f32_16x16x128_f8f6f4 v[130:133], v[2:9], v[200:207], v[130:133]
	v_mfma_f32_16x16x128_f8f6f4 v[122:125], v[10:17], v[200:207], v[122:125]
	v_mfma_f32_16x16x128_f8f6f4 v[114:117], v[2:9], v[208:215], v[114:117]
	v_mfma_f32_16x16x128_f8f6f4 v[106:109], v[10:17], v[208:215], v[106:109]
	s_setprio 0
	s_setprio 1
	v_mfma_f32_16x16x128_f8f6f4 v[146:149], v[18:25], v[184:191], v[146:149]
	v_mfma_f32_16x16x128_f8f6f4 v[142:145], v[26:33], v[184:191], v[142:145]
	v_mfma_f32_16x16x128_f8f6f4 v[134:137], v[18:25], v[192:199], v[134:137]
	v_mfma_f32_16x16x128_f8f6f4 v[126:129], v[26:33], v[192:199], v[126:129]
	v_mfma_f32_16x16x128_f8f6f4 v[118:121], v[18:25], v[200:207], v[118:121]
	v_mfma_f32_16x16x128_f8f6f4 v[110:113], v[26:33], v[200:207], v[110:113]
	v_mfma_f32_16x16x128_f8f6f4 v[102:105], v[18:25], v[208:215], v[102:105]
	v_mfma_f32_16x16x128_f8f6f4 v[98:101], v[26:33], v[208:215], v[98:101]
	s_setprio 0
	s_barrier
	s_add_i32 s44, s71, s47
	v_lshl_add_u64 v[170:171], v[170:171], 0, s[14:15]
	s_mov_b32 m0, s44
	ds_read_b128 v[184:187], v183 offset:49152
	ds_read_b128 v[188:191], v183 offset:50176
	ds_read_b128 v[192:195], v183 offset:51200
	ds_read_b128 v[196:199], v183 offset:52224
	ds_read_b128 v[200:203], v183 offset:53248
	ds_read_b128 v[204:207], v183 offset:54272
	ds_read_b128 v[208:211], v183 offset:55296
	ds_read_b128 v[212:215], v183 offset:56320
	global_load_lds_dwordx4 v[170:171], off
	s_add_i32 m0, s44, 0x2000
	s_add_u32 s42, s42, 0x158080
	v_lshl_add_u64 v[170:171], v[172:173], 0, s[14:15]
	s_addc_u32 s43, s43, 0
	s_add_i32 s44, s72, s47
	global_load_lds_dwordx4 v[170:171], off
	v_lshl_add_u64 v[170:171], s[42:43], 0, v[164:165]
	s_mov_b32 m0, s44
	s_nop 0
	global_load_lds_dwordx4 v[170:171], off
	v_lshl_add_u64 v[170:171], s[42:43], 0, v[162:163]
	s_add_i32 m0, s44, 0x2000
	s_nop 0
	global_load_lds_dwordx4 v[170:171], off
	v_lshl_add_u64 v[170:171], v[174:175], 0, s[14:15]
	s_mov_b32 m0, s57
	s_nop 0
	global_load_lds_dwordx4 v[170:171], off
	v_lshl_add_u64 v[170:171], v[176:177], 0, s[14:15]
	s_mov_b32 m0, s58
	s_nop 0
	global_load_lds_dwordx4 v[170:171], off
	s_waitcnt vmcnt(8)
	s_waitcnt lgkmcnt(0)
	s_barrier
	s_setprio 1
	v_mfma_f32_16x16x128_f8f6f4 v[94:97], v[2:9], v[184:191], v[94:97]
	v_mfma_f32_16x16x128_f8f6f4 v[90:93], v[10:17], v[184:191], v[90:93]
	v_mfma_f32_16x16x128_f8f6f4 v[82:85], v[2:9], v[192:199], v[82:85]
	v_mfma_f32_16x16x128_f8f6f4 v[74:77], v[10:17], v[192:199], v[74:77]
	v_mfma_f32_16x16x128_f8f6f4 v[66:69], v[2:9], v[200:207], v[66:69]
	v_mfma_f32_16x16x128_f8f6f4 v[58:61], v[10:17], v[200:207], v[58:61]
	v_mfma_f32_16x16x128_f8f6f4 v[50:53], v[2:9], v[208:215], v[50:53]
	v_mfma_f32_16x16x128_f8f6f4 v[42:45], v[10:17], v[208:215], v[42:45]
	s_setprio 0
	s_setprio 1
	v_mfma_f32_16x16x128_f8f6f4 v[86:89], v[18:25], v[184:191], v[86:89]
	v_mfma_f32_16x16x128_f8f6f4 v[78:81], v[26:33], v[184:191], v[78:81]
	v_mfma_f32_16x16x128_f8f6f4 v[70:73], v[18:25], v[192:199], v[70:73]
	v_mfma_f32_16x16x128_f8f6f4 v[62:65], v[26:33], v[192:199], v[62:65]
	v_mfma_f32_16x16x128_f8f6f4 v[54:57], v[18:25], v[200:207], v[54:57]
	v_mfma_f32_16x16x128_f8f6f4 v[46:49], v[26:33], v[200:207], v[46:49]
	v_mfma_f32_16x16x128_f8f6f4 v[38:41], v[18:25], v[208:215], v[38:41]
	v_mfma_f32_16x16x128_f8f6f4 v[34:37], v[26:33], v[208:215], v[34:37]
	s_setprio 0
	s_barrier
	s_add_u32 s40, s40, 0x100
	s_addc_u32 s41, s41, 0
	s_add_u32 s68, s68, 0x100
	s_addc_u32 s69, s69, 0
	s_cmp_ge_i32 s70, s39
	s_mov_b32 s42, s70
	s_cbranch_scc0 .LBB0_1690
	s_and_b64 vcc, exec, s[16:17]
	s_cbranch_vccz .LBB0_1693
	s_barrier

.LBB0_1780:
	ds_read_b128 v[24:27], v183
	ds_read_b128 v[28:31], v183 offset:1024
	ds_read_b128 v[16:19], v183 offset:2048
	ds_read_b128 v[20:23], v183 offset:3072
	ds_read_b128 v[8:11], v184
	ds_read_b128 v[12:15], v184 offset:1024
	ds_read_b128 v[0:3], v184 offset:2048
	ds_read_b128 v[4:7], v184 offset:3072
	s_add_u32 s28, s26, 0xffea8080
	s_addc_u32 s29, s27, -1
	s_cmpk_eq_i32 s56, 0x52
	s_cselect_b32 s31, s3, s29
	s_cselect_b32 s30, s2, s28
	s_cselect_b32 s29, s23, s55
	s_cselect_b32 s28, s22, s33
	v_lshl_add_u64 v[210:211], s[26:27], 0, v[164:165]
	s_add_i32 m0, s39, 0xc000
	ds_read_b128 v[172:175], v185
	ds_read_b128 v[176:179], v185 offset:1024
	ds_read_b128 v[186:189], v185 offset:2048
	ds_read_b128 v[190:193], v185 offset:3072
	ds_read_b128 v[194:197], v185 offset:4096
	ds_read_b128 v[198:201], v185 offset:5120
	ds_read_b128 v[202:205], v185 offset:6144
	ds_read_b128 v[206:209], v185 offset:7168
	global_load_lds_dwordx4 v[210:211], off
	v_lshl_add_u64 v[210:211], s[26:27], 0, v[166:167]
	s_add_i32 m0, s39, 0xe000
	s_nop 0
	global_load_lds_dwordx4 v[210:211], off
	s_waitcnt vmcnt(8)
	s_waitcnt lgkmcnt(0)
	s_barrier
	s_setprio 1
	v_mfma_f32_16x16x128_f8f6f4 v[156:159], v[24:31], v[172:179], v[156:159]
	v_mfma_f32_16x16x128_f8f6f4 v[152:155], v[16:23], v[172:179], v[152:155]
	v_mfma_f32_16x16x128_f8f6f4 v[148:151], v[24:31], v[186:193], v[148:151]
	v_mfma_f32_16x16x128_f8f6f4 v[136:139], v[16:23], v[186:193], v[136:139]
	v_mfma_f32_16x16x128_f8f6f4 v[128:131], v[24:31], v[194:201], v[128:131]
	v_mfma_f32_16x16x128_f8f6f4 v[120:123], v[16:23], v[194:201], v[120:123]
	v_mfma_f32_16x16x128_f8f6f4 v[112:115], v[24:31], v[202:209], v[112:115]
	v_mfma_f32_16x16x128_f8f6f4 v[104:107], v[16:23], v[202:209], v[104:107]
	s_setprio 0
	s_setprio 1
	v_mfma_f32_16x16x128_f8f6f4 v[144:147], v[8:15], v[172:179], v[144:147]
	v_mfma_f32_16x16x128_f8f6f4 v[140:143], v[0:7], v[172:179], v[140:143]
	v_mfma_f32_16x16x128_f8f6f4 v[132:135], v[8:15], v[186:193], v[132:135]
	v_mfma_f32_16x16x128_f8f6f4 v[124:127], v[0:7], v[186:193], v[124:127]
	v_mfma_f32_16x16x128_f8f6f4 v[116:119], v[8:15], v[194:201], v[116:119]
	v_mfma_f32_16x16x128_f8f6f4 v[108:111], v[0:7], v[194:201], v[108:111]
	v_mfma_f32_16x16x128_f8f6f4 v[100:103], v[8:15], v[202:209], v[100:103]
	v_mfma_f32_16x16x128_f8f6f4 v[96:99], v[0:7], v[202:209], v[96:99]
	s_setprio 0
	s_barrier
	s_add_i32 s57, s51, s38
	v_lshl_add_u64 v[172:173], s[28:29], 0, v[160:161]
	s_mov_b32 m0, s57
	ds_read_b128 v[186:189], v185 offset:16384
	ds_read_b128 v[190:193], v185 offset:17408
	ds_read_b128 v[194:197], v185 offset:18432
	ds_read_b128 v[198:201], v185 offset:19456
	ds_read_b128 v[202:205], v185 offset:20480
	ds_read_b128 v[206:209], v185 offset:21504
	ds_read_b128 v[210:213], v185 offset:22528
	ds_read_b128 v[214:217], v185 offset:23552
	global_load_lds_dwordx4 v[172:173], off
	s_add_i32 m0, s57, 0x2000
	s_add_u32 s58, s28, 0x158000
	v_lshl_add_u64 v[174:175], s[28:29], 0, v[162:163]
	s_addc_u32 s59, s29, 0
	s_add_i32 s57, s52, s38
	global_load_lds_dwordx4 v[174:175], off
	v_lshl_add_u64 v[176:177], s[58:59], 0, v[160:161]
	s_mov_b32 m0, s57
	v_lshl_add_u64 v[178:179], s[30:31], 0, v[162:163]
	global_load_lds_dwordx4 v[176:177], off
	v_lshl_add_u64 v[176:177], s[58:59], 0, v[162:163]
	s_add_i32 m0, s57, 0x2000
	s_nop 0
	global_load_lds_dwordx4 v[176:177], off
	v_lshl_add_u64 v[176:177], s[30:31], 0, v[160:161]
	s_mov_b32 m0, s39
	s_nop 0
	global_load_lds_dwordx4 v[176:177], off
	s_mov_b32 m0, s40
	s_nop 0
	global_load_lds_dwordx4 v[178:179], off
	s_waitcnt vmcnt(8)
	s_waitcnt lgkmcnt(0)
	s_barrier
	s_setprio 1
	v_mfma_f32_16x16x128_f8f6f4 v[92:95], v[24:31], v[186:193], v[92:95]
	v_mfma_f32_16x16x128_f8f6f4 v[88:91], v[16:23], v[186:193], v[88:91]
	v_mfma_f32_16x16x128_f8f6f4 v[80:83], v[24:31], v[194:201], v[80:83]
	v_mfma_f32_16x16x128_f8f6f4 v[72:75], v[16:23], v[194:201], v[72:75]
	v_mfma_f32_16x16x128_f8f6f4 v[64:67], v[24:31], v[202:209], v[64:67]
	v_mfma_f32_16x16x128_f8f6f4 v[56:59], v[16:23], v[202:209], v[56:59]
	v_mfma_f32_16x16x128_f8f6f4 v[48:51], v[24:31], v[210:217], v[48:51]
	v_mfma_f32_16x16x128_f8f6f4 v[40:43], v[16:23], v[210:217], v[40:43]
	s_setprio 0
	s_setprio 1
	v_mfma_f32_16x16x128_f8f6f4 v[84:87], v[8:15], v[186:193], v[84:87]
	v_mfma_f32_16x16x128_f8f6f4 v[76:79], v[0:7], v[186:193], v[76:79]
	v_mfma_f32_16x16x128_f8f6f4 v[68:71], v[8:15], v[194:201], v[68:71]
	v_mfma_f32_16x16x128_f8f6f4 v[60:63], v[0:7], v[194:201], v[60:63]
	v_mfma_f32_16x16x128_f8f6f4 v[52:55], v[8:15], v[202:209], v[52:55]
	v_mfma_f32_16x16x128_f8f6f4 v[44:47], v[0:7], v[202:209], v[44:47]
	v_mfma_f32_16x16x128_f8f6f4 v[36:39], v[8:15], v[210:217], v[36:39]
	v_mfma_f32_16x16x128_f8f6f4 v[32:35], v[0:7], v[210:217], v[32:35]
	s_setprio 0
	s_barrier
	s_add_i32 s57, 0, 0x18000
	s_add_i32 s58, 0, 0x1c000
	v_add_u32_e32 v12, s57, v182
	v_add_u32_e32 v28, s58, v182
	ds_read_b128 v[0:3], v12
	ds_read_b128 v[4:7], v12 offset:1024
	ds_read_b128 v[8:11], v12 offset:2048
	ds_read_b128 v[12:15], v12 offset:3072
	ds_read_b128 v[16:19], v28
	ds_read_b128 v[20:23], v28 offset:1024
	ds_read_b128 v[24:27], v28 offset:2048
	ds_read_b128 v[28:31], v28 offset:3072
	s_add_u32 s30, s30, 0x158000
	s_addc_u32 s31, s31, 0
	s_mov_b32 m0, s41
	v_lshl_add_u64 v[218:219], s[30:31], 0, v[160:161]
	ds_read_b128 v[186:189], v185 offset:32768
	ds_read_b128 v[190:193], v185 offset:33792
	ds_read_b128 v[194:197], v185 offset:34816
	ds_read_b128 v[198:201], v185 offset:35840
	ds_read_b128 v[202:205], v185 offset:36864
	ds_read_b128 v[206:209], v185 offset:37888
	ds_read_b128 v[210:213], v185 offset:38912
	ds_read_b128 v[214:217], v185 offset:39936
	global_load_lds_dwordx4 v[218:219], off
	v_lshl_add_u64 v[218:219], s[30:31], 0, v[162:163]
	s_mov_b32 m0, s42
	s_nop 0
	global_load_lds_dwordx4 v[218:219], off
	s_waitcnt vmcnt(8)
	s_waitcnt lgkmcnt(0)
	s_barrier
	s_setprio 1
	v_mfma_f32_16x16x128_f8f6f4 v[156:159], v[0:7], v[186:193], v[156:159]
	v_mfma_f32_16x16x128_f8f6f4 v[152:155], v[8:15], v[186:193], v[152:155]
	v_mfma_f32_16x16x128_f8f6f4 v[148:151], v[0:7], v[194:201], v[148:151]
	v_mfma_f32_16x16x128_f8f6f4 v[136:139], v[8:15], v[194:201], v[136:139]
	v_mfma_f32_16x16x128_f8f6f4 v[128:131], v[0:7], v[202:209], v[128:131]
	v_mfma_f32_16x16x128_f8f6f4 v[120:123], v[8:15], v[202:209], v[120:123]
	v_mfma_f32_16x16x128_f8f6f4 v[112:115], v[0:7], v[210:217], v[112:115]
	v_mfma_f32_16x16x128_f8f6f4 v[104:107], v[8:15], v[210:217], v[104:107]
	s_setprio 0
	s_setprio 1
	v_mfma_f32_16x16x128_f8f6f4 v[144:147], v[16:23], v[186:193], v[144:147]
	v_mfma_f32_16x16x128_f8f6f4 v[140:143], v[24:31], v[186:193], v[140:143]
	v_mfma_f32_16x16x128_f8f6f4 v[132:135], v[16:23], v[194:201], v[132:135]
	v_mfma_f32_16x16x128_f8f6f4 v[124:127], v[24:31], v[194:201], v[124:127]
	v_mfma_f32_16x16x128_f8f6f4 v[116:119], v[16:23], v[202:209], v[116:119]
	v_mfma_f32_16x16x128_f8f6f4 v[108:111], v[24:31], v[202:209], v[108:111]
	v_mfma_f32_16x16x128_f8f6f4 v[100:103], v[16:23], v[210:217], v[100:103]
	v_mfma_f32_16x16x128_f8f6f4 v[96:99], v[24:31], v[210:217], v[96:99]
	s_setprio 0
	s_barrier
	s_add_i32 s30, s57, s38
	v_lshl_add_u64 v[172:173], v[172:173], 0, s[8:9]
	s_mov_b32 m0, s30
	ds_read_b128 v[186:189], v185 offset:49152
	ds_read_b128 v[190:193], v185 offset:50176
	ds_read_b128 v[194:197], v185 offset:51200
	ds_read_b128 v[198:201], v185 offset:52224
	ds_read_b128 v[202:205], v185 offset:53248
	ds_read_b128 v[206:209], v185 offset:54272
	ds_read_b128 v[210:213], v185 offset:55296
	ds_read_b128 v[214:217], v185 offset:56320
	global_load_lds_dwordx4 v[172:173], off
	s_add_i32 m0, s30, 0x2000
	s_add_u32 s28, s28, 0x158080
	v_lshl_add_u64 v[172:173], v[174:175], 0, s[8:9]
	s_addc_u32 s29, s29, 0
	s_add_i32 s30, s58, s38
	global_load_lds_dwordx4 v[172:173], off
	v_lshl_add_u64 v[172:173], s[28:29], 0, v[160:161]
	s_mov_b32 m0, s30
	s_nop 0
	global_load_lds_dwordx4 v[172:173], off
	v_lshl_add_u64 v[172:173], s[28:29], 0, v[162:163]
	s_add_i32 m0, s30, 0x2000
	s_nop 0
	global_load_lds_dwordx4 v[172:173], off
	v_lshl_add_u64 v[172:173], v[176:177], 0, s[8:9]
	s_mov_b32 m0, s48
	s_nop 0
	global_load_lds_dwordx4 v[172:173], off
	v_lshl_add_u64 v[172:173], v[178:179], 0, s[8:9]
	s_mov_b32 m0, s49
	s_nop 0
	global_load_lds_dwordx4 v[172:173], off
	s_waitcnt vmcnt(8)
	s_waitcnt lgkmcnt(0)
	s_barrier
	s_setprio 1
	v_mfma_f32_16x16x128_f8f6f4 v[92:95], v[0:7], v[186:193], v[92:95]
	v_mfma_f32_16x16x128_f8f6f4 v[88:91], v[8:15], v[186:193], v[88:91]
	v_mfma_f32_16x16x128_f8f6f4 v[80:83], v[0:7], v[194:201], v[80:83]
	v_mfma_f32_16x16x128_f8f6f4 v[72:75], v[8:15], v[194:201], v[72:75]
	v_mfma_f32_16x16x128_f8f6f4 v[64:67], v[0:7], v[202:209], v[64:67]
	v_mfma_f32_16x16x128_f8f6f4 v[56:59], v[8:15], v[202:209], v[56:59]
	v_mfma_f32_16x16x128_f8f6f4 v[48:51], v[0:7], v[210:217], v[48:51]
	v_mfma_f32_16x16x128_f8f6f4 v[40:43], v[8:15], v[210:217], v[40:43]
	s_setprio 0
	s_setprio 1
	v_mfma_f32_16x16x128_f8f6f4 v[84:87], v[16:23], v[186:193], v[84:87]
	v_mfma_f32_16x16x128_f8f6f4 v[76:79], v[24:31], v[186:193], v[76:79]
	v_mfma_f32_16x16x128_f8f6f4 v[68:71], v[16:23], v[194:201], v[68:71]
	v_mfma_f32_16x16x128_f8f6f4 v[60:63], v[24:31], v[194:201], v[60:63]
	v_mfma_f32_16x16x128_f8f6f4 v[52:55], v[16:23], v[202:209], v[52:55]
	v_mfma_f32_16x16x128_f8f6f4 v[44:47], v[24:31], v[202:209], v[44:47]
	v_mfma_f32_16x16x128_f8f6f4 v[36:39], v[16:23], v[210:217], v[36:39]
	v_mfma_f32_16x16x128_f8f6f4 v[32:35], v[24:31], v[210:217], v[32:35]
	s_setprio 0
	s_barrier
	s_add_i32 s56, s56, 2
	s_add_u32 s26, s26, 0x100
	s_addc_u32 s27, s27, 0
	s_add_u32 s33, s33, 0x100
	s_addc_u32 s55, s55, 0
	s_cmpk_gt_u32 s56, 0x53
	s_cbranch_scc0 .LBB0_1780
	s_and_b64 vcc, exec, s[10:11]
	s_cbranch_vccz .LBB0_1783
	s_barrier
